# plus LRU r-gate fold (fma+rcp), 24-bit row multiplies in LRU loads, P6 epilogue store addresses by one 64-bit add
# speedup vs baseline: 1.0120x; 1.0041x over previous
.LBB0_314:
	s_or_b64 exec, exec, s[48:49]
	s_waitcnt vmcnt(60)
	v_bfe_u32 v52, v45, 16, 1
	v_bfe_u32 v53, v44, 16, 1
	v_bfe_u32 v54, v25, 16, 1
	v_bfe_u32 v55, v24, 16, 1
	v_bfe_u32 v57, v21, 16, 1
	v_bfe_u32 v61, v20, 16, 1
	v_bfe_u32 v17, v19, 16, 1
	v_bfe_u32 v16, v18, 16, 1
	v_add3_u32 v16, v18, v16, s64
	v_add3_u32 v17, v19, v17, s64
	v_add3_u32 v18, v20, v61, s64
	v_add3_u32 v19, v21, v57, s64
	v_add3_u32 v20, v24, v55, s64
	v_add3_u32 v21, v25, v54, s64
	v_add3_u32 v24, v44, v53, s64
	v_add3_u32 v25, v45, v52, s64
	s_waitcnt vmcnt(53)
	v_bfe_u32 v45, v30, 16, 1
	v_bfe_u32 v52, v29, 16, 1
	v_bfe_u32 v53, v28, 16, 1
	v_bfe_u32 v55, v26, 16, 1
	v_add3_u32 v26, v26, v55, s64
	v_add3_u32 v28, v28, v53, s64
	v_add3_u32 v29, v29, v52, s64
	v_add3_u32 v30, v30, v45, s64
	s_waitcnt vmcnt(37)
	v_bfe_u32 v52, v50, 16, 1
	v_bfe_u32 v53, v49, 16, 1
	v_bfe_u32 v55, v47, 16, 1
	v_bfe_u32 v45, v46, 16, 1
	v_bfe_u32 v54, v27, 16, 1
	v_add3_u32 v45, v46, v45, s64
	v_add3_u32 v46, v47, v55, s64
	v_add3_u32 v47, v49, v53, s64
	v_add3_u32 v49, v50, v52, s64
	v_bfe_u32 v52, v33, 16, 1
	v_add3_u32 v27, v27, v54, s64
	v_bfe_u32 v54, v48, 16, 1
	v_bfe_u32 v53, v36, 16, 1
	v_add3_u32 v52, v33, v52, s64
	s_waitcnt vmcnt(21)
	v_bfe_u32 v33, v86, 16, 1
	v_add3_u32 v48, v48, v54, s64
	v_bfe_u32 v54, v37, 16, 1
	v_add3_u32 v53, v36, v53, s64
	v_bfe_u32 v36, v83, 16, 1
	v_add3_u32 v102, v86, v33, s64
	s_waitcnt vmcnt(20)
	v_bfe_u32 v33, v76, 16, 1
	v_add3_u32 v54, v37, v54, s64
	v_bfe_u32 v37, v66, 16, 1
	v_add3_u32 v100, v83, v36, s64
	v_bfe_u32 v36, v73, 16, 1
	v_add3_u32 v123, v76, v33, s64
	s_waitcnt vmcnt(6)
	v_bfe_u32 v33, v92, 16, 1
	v_add3_u32 v66, v66, v37, s64
	v_bfe_u32 v37, v71, 16, 1
	v_add3_u32 v119, v73, v36, s64
	v_bfe_u32 v36, v91, 16, 1
	v_add3_u32 v139, v92, v33, s64
	s_waitcnt vmcnt(4)
	v_bfe_u32 v33, v88, 16, 1
	v_add3_u32 v103, v71, v37, s64
	v_bfe_u32 v37, v90, 16, 1
	v_add3_u32 v137, v91, v36, s64
	v_bfe_u32 v36, v85, 16, 1
	v_add3_u32 v151, v88, v33, s64
	s_waitcnt vmcnt(1)
	v_mul_f32_e64 v33, |v79|, s65
	v_add3_u32 v131, v90, v37, s64
	v_bfe_u32 v37, v81, 16, 1
	v_add3_u32 v149, v85, v36, s64
	v_rndne_f32_e32 v36, v33
	v_add3_u32 v147, v81, v37, s64
	v_sub_f32_e32 v37, v33, v36
	v_fma_f32 v33, |v79|, s65, -v33
	v_fma_f32 v33, |v79|, s66, v33
	v_add_f32_e32 v33, v37, v33
	v_exp_f32_e32 v33, v33
	v_cvt_i32_f32_e32 v36, v36
	v_bfe_u32 v44, v31, 16, 1
	v_bfe_u32 v57, v23, 16, 1
	v_bfe_u32 v61, v22, 16, 1
	v_ldexp_f32 v33, v33, v36
	v_cmp_ngt_f32_e64 vcc, |v79|, s67
	v_add3_u32 v22, v22, v61, s64
	v_add3_u32 v23, v23, v57, s64
	v_add3_u32 v31, v31, v44, s64
	v_bfe_u32 v44, v42, 16, 1
	v_bfe_u32 v57, v35, 16, 1
	v_bfe_u32 v61, v34, 16, 1
	v_cndmask_b32_e32 v33, 0, v33, vcc
	v_cmp_nlt_f32_e64 vcc, |v79|, s75
	v_add3_u32 v34, v34, v61, s64
	v_add3_u32 v35, v35, v57, s64
	v_add3_u32 v44, v42, v44, s64
	v_bfe_u32 v42, v58, 16, 1
	v_bfe_u32 v61, v51, 16, 1
	v_bfe_u32 v57, v43, 16, 1
	v_bfe_u32 v55, v38, 16, 1
	v_cndmask_b32_e32 v153, v211, v33, vcc
	v_add3_u32 v55, v38, v55, s64
	v_add3_u32 v57, v43, v57, s64
	v_add3_u32 v51, v51, v61, s64
	v_add3_u32 v61, v58, v42, s64
	v_bfe_u32 v38, v63, 16, 1
	v_bfe_u32 v42, v60, 16, 1
	v_bfe_u32 v43, v59, 16, 1
	v_bfe_u32 v58, v56, 16, 1
	v_add_f32_e32 v33, 1.0, v153
	v_add3_u32 v56, v56, v58, s64
	v_add3_u32 v58, v59, v43, s64
	v_add3_u32 v59, v60, v42, s64
	v_add3_u32 v64, v63, v38, s64
	v_bfe_u32 v38, v69, 16, 1
	v_bfe_u32 v60, v39, 16, 1
	v_max_f32_e64 v37, -v79, -v79
	v_add_f32_e32 v36, -1.0, v33
	v_add3_u32 v60, v39, v60, s64
	v_add3_u32 v101, v69, v38, s64
	v_bfe_u32 v38, v87, 16, 1
	v_bfe_u32 v39, v84, 16, 1
	v_max_f32_e32 v117, 0, v37
	v_sub_f32_e32 v37, v36, v33
	v_add3_u32 v127, v84, v39, s64
	v_add3_u32 v129, v87, v38, s64
	v_bfe_u32 v38, v78, 16, 1
	v_bfe_u32 v39, v75, 16, 1
	v_add_f32_e32 v37, 1.0, v37
	v_sub_f32_e32 v36, v153, v36
	v_add3_u32 v143, v75, v39, s64
	v_add3_u32 v145, v78, v38, s64
	v_add_f32_e32 v38, v36, v37
	v_frexp_mant_f32_e32 v39, v33
	v_cvt_f64_f32_e32 v[36:37], v33
	v_frexp_exp_i32_f64_e32 v36, v[36:37]
	v_cmp_gt_f32_e32 vcc, s79, v39
	v_bfe_u32 v43, v41, 16, 1
	v_bfe_u32 v42, v65, 16, 1
	v_subbrev_co_u32_e32 v36, vcc, 0, v36, vcc
	v_add3_u32 v63, v41, v43, s64
	v_bfe_u32 v41, v77, 16, 1
	v_sub_u32_e32 v37, 0, v36
	v_add3_u32 v65, v65, v42, s64
	v_bfe_u32 v42, v74, 16, 1
	v_add3_u32 v121, v77, v41, s64
	v_bfe_u32 v41, v70, 16, 1
	v_ldexp_f32 v33, v33, v37
	v_add3_u32 v115, v74, v42, s64
	v_bfe_u32 v42, v68, 16, 1
	v_add3_u32 v135, v70, v41, s64
	v_ldexp_f32 v37, v38, v37
	v_add_f32_e32 v38, -1.0, v33
	v_add_f32_e32 v41, 1.0, v33
	v_bfe_u32 v50, v40, 16, 1
	v_add3_u32 v133, v68, v42, s64
	v_add_f32_e32 v39, 1.0, v38
	v_add_f32_e32 v42, -1.0, v41
	v_add3_u32 v50, v40, v50, s64
	v_bfe_u32 v40, v62, 16, 1
	v_sub_f32_e32 v39, v33, v39
	v_sub_f32_e32 v33, v33, v42
	v_add3_u32 v62, v62, v40, s64
	v_bfe_u32 v40, v67, 16, 1
	v_add_f32_e32 v33, v37, v33
	v_add3_u32 v67, v67, v40, s64
	v_bfe_u32 v40, v80, 16, 1
	v_add_f32_e32 v39, v37, v39
	v_add_f32_e32 v37, v41, v33
	v_add3_u32 v125, v80, v40, s64
	v_bfe_u32 v40, v72, 16, 1
	v_rcp_f32_e32 v42, v37
	v_add3_u32 v141, v72, v40, s64
	v_add_f32_e32 v40, v38, v39
	v_sub_f32_e32 v38, v38, v40
	v_add_f32_e32 v38, v39, v38
	v_sub_f32_e32 v39, v41, v37
	v_add_f32_e32 v33, v33, v39
	v_mul_f32_e32 v39, v40, v42
	v_mul_f32_e32 v41, v37, v39
	v_fma_f32 v43, v39, v37, -v41
	v_fmac_f32_e32 v43, v39, v33
	v_add_f32_e32 v68, v41, v43
	v_sub_f32_e32 v69, v40, v68
	v_sub_f32_e32 v40, v40, v69
	v_sub_f32_e32 v41, v68, v41
	v_sub_f32_e32 v40, v40, v68
	v_add_f32_e32 v38, v38, v40
	v_sub_f32_e32 v40, v41, v43
	v_add_f32_e32 v38, v40, v38
	v_add_f32_e32 v40, v69, v38
	v_mul_f32_e32 v41, v42, v40
	v_mul_f32_e32 v43, v37, v41
	v_fma_f32 v37, v41, v37, -v43
	v_fmac_f32_e32 v37, v41, v33
	v_sub_f32_e32 v33, v69, v40
	v_add_f32_e32 v33, v38, v33
	v_add_f32_e32 v38, v43, v37
	v_sub_f32_e32 v68, v40, v38
	v_sub_f32_e32 v40, v40, v68
	v_sub_f32_e32 v43, v38, v43
	v_sub_f32_e32 v38, v40, v38
	v_add_f32_e32 v33, v33, v38
	v_sub_f32_e32 v37, v43, v37
	v_cvt_f32_i32_e32 v36, v36
	v_add_f32_e32 v33, v37, v33
	v_add_f32_e32 v37, v39, v41
	v_add_f32_e32 v33, v68, v33
	v_sub_f32_e32 v38, v37, v39
	v_mul_f32_e32 v33, v42, v33
	v_sub_f32_e32 v38, v41, v38
	v_add_f32_e32 v33, v38, v33
	v_mul_f32_e32 v41, 0x3f317218, v36
	v_add_f32_e32 v38, v37, v33
	v_fma_f32 v42, v36, s80, -v41
	v_fmac_f32_e32 v42, 0xb102e308, v36
	v_sub_f32_e32 v36, v38, v37
	v_mul_f32_e32 v39, v38, v38
	v_sub_f32_e32 v33, v33, v36
	v_add_f32_e32 v36, v41, v42
	v_fmamk_f32 v40, v39, 0x3e9b6dac, v208
	v_sub_f32_e32 v37, v36, v41
	v_fmaak_f32 v40, v39, v40, 0x3f2aaada
	v_sub_f32_e32 v155, v42, v37
	v_ldexp_f32 v37, v38, 1
	v_mul_f32_e32 v38, v38, v39
	v_mul_f32_e32 v38, v38, v40
	v_add_f32_e32 v39, v37, v38
	v_sub_f32_e32 v37, v39, v37
	v_ldexp_f32 v33, v33, 1
	v_sub_f32_e32 v37, v38, v37
	v_add_f32_e32 v33, v33, v37
	v_add_f32_e32 v37, v39, v33
	v_sub_f32_e32 v38, v37, v39
	v_add_f32_e32 v159, v36, v37
	v_sub_f32_e32 v157, v33, v38
	v_sub_f32_e32 v33, v159, v36
	v_sub_f32_e32 v38, v159, v33
	v_sub_f32_e32 v40, v36, v38
	v_sub_u32_e32 v36, 0x7bf, v170
	v_cndmask_b32_e64 v36, v36, v193, s[12:13]
	v_mul_u32_u24_e32 v36, 0x700, v36
	v_sub_f32_e32 v33, v37, v33
	v_lshlrev_b32_e32 v36, 1, v36
	v_mov_b32_e32 v37, v32
	v_lshl_add_u64 v[72:73], v[164:165], 0, v[36:37]
	global_load_dwordx4 v[36:39], v[72:73], off offset:-2048
	v_lshl_add_u64 v[68:69], v[72:73], 0, s[40:41]
	v_add_f32_e32 v161, v33, v40
	global_load_dwordx4 v[40:43], v[72:73], off offset:1536
	s_nop 0
	global_load_dwordx4 v[68:71], v[68:69], off offset:3584
	v_add_co_u32_e32 v72, vcc, s82, v72
	v_mul_f32_e32 v111, 0xbfb8aa3b, v89
	s_nop 0
	v_addc_co_u32_e32 v73, vcc, 0, v73, vcc
	global_load_dwordx4 v[72:75], v[72:73], off offset:512
	v_mul_f32_e32 v113, 0xbfb8aa3b, v82
	s_waitcnt lgkmcnt(0)
	s_barrier
	ds_read_b128 v[76:79], v176 offset:40960
	ds_read_b128 v[80:83], v176 offset:40976
	ds_read_b128 v[84:87], v176 offset:41216
	ds_read_b128 v[88:91], v176 offset:41232
	ds_read_b128 v[92:95], v176 offset:41472
	ds_read_b128 v[96:99], v176 offset:41488
	ds_read_b128 v[214:217], v176 offset:41984
	ds_read_b128 v[218:221], v176 offset:41728
	ds_read_b128 v[222:225], v176 offset:41744
	ds_read_b128 v[226:229], v176 offset:42000
	v_lshlrev_b32_e32 v166, 16, v4
	v_and_b32_e32 v167, 0xffff0000, v4
	v_lshlrev_b32_e32 v4, 16, v5
	v_and_b32_e32 v5, 0xffff0000, v5
	s_waitcnt lgkmcnt(3)
	v_pk_fma_f32 v[166:167], v[76:77], v[166:167], v[214:215]
	s_waitcnt vmcnt(4)
	v_lshlrev_b32_e32 v172, 16, v12
	v_and_b32_e32 v173, 0xffff0000, v12
	v_pk_fma_f32 v[4:5], v[78:79], v[4:5], v[216:217]
	v_lshlrev_b32_e32 v12, 16, v13
	v_and_b32_e32 v13, 0xffff0000, v13
	v_pk_fma_f32 v[166:167], v[84:85], v[172:173], v[166:167]
	v_lshlrev_b32_e32 v172, 16, v8
	v_and_b32_e32 v173, 0xffff0000, v8
	v_pk_fma_f32 v[4:5], v[86:87], v[12:13], v[4:5]
	v_lshlrev_b32_e32 v8, 16, v9
	v_and_b32_e32 v9, 0xffff0000, v9
	v_pk_fma_f32 v[166:167], v[92:93], v[172:173], v[166:167]
	v_lshlrev_b32_e32 v172, 16, v0
	v_and_b32_e32 v173, 0xffff0000, v0
	v_pk_fma_f32 v[4:5], v[94:95], v[8:9], v[4:5]
	v_lshlrev_b32_e32 v0, 16, v1
	v_and_b32_e32 v1, 0xffff0000, v1
	s_waitcnt lgkmcnt(2)
	v_pk_fma_f32 v[4:5], v[220:221], v[0:1], v[4:5]
	v_lshlrev_b32_e32 v0, 16, v6
	v_and_b32_e32 v1, 0xffff0000, v6
	s_waitcnt lgkmcnt(0)
	v_pk_fma_f32 v[0:1], v[80:81], v[0:1], v[226:227]
	v_lshlrev_b32_e32 v8, 16, v14
	v_and_b32_e32 v9, 0xffff0000, v14
	v_pk_fma_f32 v[0:1], v[88:89], v[8:9], v[0:1]
	v_lshlrev_b32_e32 v8, 16, v10
	v_and_b32_e32 v9, 0xffff0000, v10
	v_pk_fma_f32 v[0:1], v[96:97], v[8:9], v[0:1]
	v_lshlrev_b32_e32 v8, 16, v2
	v_and_b32_e32 v9, 0xffff0000, v2
	v_pk_fma_f32 v[8:9], v[222:223], v[8:9], v[0:1]
	v_lshlrev_b32_e32 v0, 16, v7
	v_and_b32_e32 v1, 0xffff0000, v7
	v_pk_fma_f32 v[0:1], v[82:83], v[0:1], v[228:229]
	v_lshlrev_b32_e32 v6, 16, v15
	v_and_b32_e32 v7, 0xffff0000, v15
	v_pk_fma_f32 v[0:1], v[90:91], v[6:7], v[0:1]
	v_lshlrev_b32_e32 v6, 16, v11
	v_and_b32_e32 v7, 0xffff0000, v11
	v_pk_fma_f32 v[0:1], v[98:99], v[6:7], v[0:1]
	v_lshlrev_b32_e32 v2, 16, v3
	v_and_b32_e32 v3, 0xffff0000, v3
	v_pk_fma_f32 v[166:167], v[218:219], v[172:173], v[166:167]
	v_pk_fma_f32 v[6:7], v[224:225], v[2:3], v[0:1]
	v_cvt_pk_bf16_f32 v0, v166, v167
	v_cvt_pk_bf16_f32 v1, v4, v5
	v_cvt_pk_bf16_f32 v2, v8, v9
	v_cvt_pk_bf16_f32 v3, v6, v7
	v_add_u32_e32 v33, v177, v178
	ds_write_b128 v33, v[0:3]
	v_add_f32_e32 v163, v155, v157
	v_sub_f32_e32 v174, v163, v155
	v_sub_f32_e32 v175, v163, v174
	v_perm_b32 v47, v49, v47, s84
	v_perm_b32 v46, v48, v46, s84
	v_perm_b32 v45, v45, v44, s84
	v_perm_b32 v44, v35, v34, s84
	v_perm_b32 v51, v61, v51, s84
	v_perm_b32 v50, v57, v50, s84
	v_perm_b32 v49, v55, v54, s84
	v_perm_b32 v48, v53, v52, s84
	s_waitcnt vmcnt(3)
	v_lshlrev_b32_e32 v0, 16, v36
	v_and_b32_e32 v1, 0xffff0000, v36
	v_pk_fma_f32 v[0:1], v[76:77], v[0:1], v[214:215]
	s_waitcnt vmcnt(2)
	v_lshlrev_b32_e32 v2, 16, v40
	v_and_b32_e32 v3, 0xffff0000, v40
	v_pk_fma_f32 v[0:1], v[84:85], v[2:3], v[0:1]
	s_waitcnt vmcnt(1)
	v_lshlrev_b32_e32 v2, 16, v68
	v_and_b32_e32 v3, 0xffff0000, v68
	v_pk_fma_f32 v[0:1], v[92:93], v[2:3], v[0:1]
	s_waitcnt vmcnt(0)
	v_lshlrev_b32_e32 v2, 16, v72
	v_and_b32_e32 v3, 0xffff0000, v72
	v_pk_fma_f32 v[0:1], v[218:219], v[2:3], v[0:1]
	v_lshlrev_b32_e32 v2, 16, v37
	v_and_b32_e32 v3, 0xffff0000, v37
	v_pk_fma_f32 v[2:3], v[78:79], v[2:3], v[216:217]
	v_lshlrev_b32_e32 v4, 16, v41
	v_and_b32_e32 v5, 0xffff0000, v41
	v_pk_fma_f32 v[2:3], v[86:87], v[4:5], v[2:3]
	v_lshlrev_b32_e32 v4, 16, v69
	v_and_b32_e32 v5, 0xffff0000, v69
	v_pk_fma_f32 v[2:3], v[94:95], v[4:5], v[2:3]
	v_lshlrev_b32_e32 v4, 16, v73
	v_and_b32_e32 v5, 0xffff0000, v73
	v_pk_fma_f32 v[2:3], v[220:221], v[4:5], v[2:3]
	v_lshlrev_b32_e32 v4, 16, v38
	v_and_b32_e32 v5, 0xffff0000, v38
	v_pk_fma_f32 v[4:5], v[80:81], v[4:5], v[226:227]
	v_lshlrev_b32_e32 v6, 16, v42
	v_and_b32_e32 v7, 0xffff0000, v42
	v_pk_fma_f32 v[4:5], v[88:89], v[6:7], v[4:5]
	v_lshlrev_b32_e32 v6, 16, v70
	v_and_b32_e32 v7, 0xffff0000, v70
	v_pk_fma_f32 v[4:5], v[96:97], v[6:7], v[4:5]
	v_lshlrev_b32_e32 v6, 16, v74
	v_and_b32_e32 v7, 0xffff0000, v74
	v_pk_fma_f32 v[4:5], v[222:223], v[6:7], v[4:5]
	v_lshlrev_b32_e32 v6, 16, v39
	v_and_b32_e32 v7, 0xffff0000, v39
	v_pk_fma_f32 v[6:7], v[82:83], v[6:7], v[228:229]
	v_lshlrev_b32_e32 v8, 16, v43
	v_and_b32_e32 v9, 0xffff0000, v43
	v_pk_fma_f32 v[6:7], v[90:91], v[8:9], v[6:7]
	v_lshlrev_b32_e32 v8, 16, v71
	v_and_b32_e32 v9, 0xffff0000, v71
	v_pk_fma_f32 v[6:7], v[98:99], v[8:9], v[6:7]
	v_lshlrev_b32_e32 v8, 16, v75
	v_and_b32_e32 v9, 0xffff0000, v75
	v_pk_fma_f32 v[6:7], v[224:225], v[8:9], v[6:7]
	v_cvt_pk_bf16_f32 v0, v0, v1
	v_cvt_pk_bf16_f32 v1, v2, v3
	v_cvt_pk_bf16_f32 v2, v4, v5
	v_cvt_pk_bf16_f32 v3, v6, v7
	ds_write_b128 v33, v[0:3] offset:9216
	v_cndmask_b32_e64 v2, v254, v179, s[12:13]
	v_add_u32_e32 v0, -1, v2
	v_mul_u32_u24_e32 v2, 0xe00, v2
	v_mov_b32_e32 v3, v32
	v_mad_u64_u32 v[0:1], s[14:15], v0, s83, v[164:165]
	v_lshl_add_u64 v[2:3], v[164:165], 0, v[2:3]
	v_lshl_add_u64 v[4:5], v[2:3], 0, s[40:41]
	global_load_dwordx4 v[96:99], v[0:1], off offset:1536
	global_load_dwordx4 v[92:95], v[2:3], off offset:1536
	v_add_co_u32_e32 v0, vcc, s82, v2
	v_cndmask_b32_e64 v2, v182, v168, s[12:13]
	s_nop 0
	v_addc_co_u32_e32 v1, vcc, 0, v3, vcc
	global_load_dwordx4 v[88:91], v[4:5], off offset:3584
	global_load_dwordx4 v[84:87], v[0:1], off offset:512
	v_add_u32_e32 v0, -1, v2
	v_mul_u32_u24_e32 v2, 0xe00, v2
	v_mov_b32_e32 v3, v32
	v_mad_u64_u32 v[0:1], s[14:15], v0, s83, v[164:165]
	v_lshl_add_u64 v[2:3], v[164:165], 0, v[2:3]
	v_lshl_add_u64 v[4:5], v[2:3], 0, s[40:41]
	global_load_dwordx4 v[80:83], v[0:1], off offset:1536
	global_load_dwordx4 v[76:79], v[2:3], off offset:1536
	v_add_co_u32_e32 v0, vcc, s82, v2
	v_perm_b32 v39, v25, v24, s84
	s_nop 0
	v_addc_co_u32_e32 v1, vcc, 0, v3, vcc
	global_load_dwordx4 v[72:75], v[4:5], off offset:3584
	global_load_dwordx4 v[68:71], v[0:1], off offset:512
	s_waitcnt lgkmcnt(0)
	s_barrier
	ds_read_b128 v[214:217], v213
	ds_read_b128 v[218:221], v213 offset:32
	v_sub_f32_e32 v0, v155, v175
	v_sub_f32_e32 v1, v157, v174
	v_perm_b32 v38, v21, v20, s84
	v_perm_b32 v37, v19, v18, s84
	v_perm_b32 v36, v17, v16, s84
	v_add_f32_e32 v155, v1, v0
	v_perm_b32 v43, v31, v30, s84
	s_waitcnt lgkmcnt(1)
	v_mfma_f32_32x32x16_bf16 v[0:15], v[214:217], v[36:39], 0
	v_perm_b32 v42, v29, v28, s84
	v_perm_b32 v41, v27, v26, s84
	v_perm_b32 v40, v23, v22, s84
	v_perm_b32 v55, v102, v100, s84
	v_perm_b32 v54, v66, v64, s84
	v_perm_b32 v53, v62, v59, s84
	v_perm_b32 v52, v58, v56, s84
	v_mfma_f32_32x32x16_bf16 v[16:31], v[214:217], v[40:43], 0
	ds_read_b128 v[214:217], v213 offset:64
	v_perm_b32 v59, v123, v119, s84
	v_perm_b32 v58, v103, v101, s84
	v_perm_b32 v57, v67, v65, s84
	v_perm_b32 v56, v63, v60, s84
	v_perm_b32 v63, v139, v137, s84
	v_perm_b32 v62, v131, v129, s84
	s_waitcnt lgkmcnt(1)
	v_mfma_f32_32x32x16_bf16 v[0:15], v[218:221], v[44:47], v[0:15]
	v_perm_b32 v61, v127, v125, s84
	v_perm_b32 v60, v121, v115, s84
	v_perm_b32 v67, v151, v149, s84
	v_perm_b32 v66, v147, v145, s84
	v_perm_b32 v65, v143, v141, s84
	v_perm_b32 v64, v135, v133, s84
	v_add_f32_e32 v157, v163, v161
	v_mfma_f32_32x32x16_bf16 v[16:31], v[218:221], v[48:51], v[16:31]
	ds_read_b128 v[218:221], v213 offset:96
	v_add_f32_e32 v161, v159, v157
	v_sub_f32_e32 v159, v161, v159
	v_sub_f32_e32 v157, v157, v159
	v_add_f32_e32 v155, v155, v157
	v_add_f32_e32 v155, v161, v155
	v_cmp_neq_f32_e32 vcc, s78, v153
	s_waitcnt lgkmcnt(1)
	v_mfma_f32_32x32x16_bf16 v[0:15], v[214:217], v[52:55], v[0:15]
	v_and_b32_e32 v35, 64, v212
	v_cndmask_b32_e32 v34, v211, v155, vcc
	v_cmp_lt_f32_e64 vcc, |v153|, s81
	v_add_u32_e32 v35, 64, v35
	v_add_u32_e32 v100, v200, v190
	v_cndmask_b32_e32 v34, v34, v153, vcc
	v_add_f32_e32 v34, v117, v34
	v_mfma_f32_32x32x16_bf16 v[16:31], v[214:217], v[56:59], v[16:31]
	v_mul_f32_e32 v34, 0xc1000000, v34
	v_mul_f32_e32 v117, 0x3fb8aa3b, v34
	v_rcp_f32_e32 v117, v117
	s_nop 0
	v_xor_b32_e32 v34, 32, v212
	v_cmp_lt_i32_e32 vcc, v34, v35
	s_nop 1
	v_cndmask_b32_e32 v34, v212, v34, vcc
	s_waitcnt lgkmcnt(0)
	v_mfma_f32_32x32x16_bf16 v[0:15], v[218:221], v[60:63], v[0:15]
	v_lshlrev_b32_e32 v115, 2, v34
	v_mfma_f32_32x32x16_bf16 v[16:31], v[218:221], v[64:67], v[16:31]
	s_nop 9
	v_fmamk_f32 v0, v0, 0xbfb8aa3b, v111
	v_exp_f32_e32 v0, v0
	v_fmamk_f32 v1, v1, 0xbfb8aa3b, v111
	v_exp_f32_e32 v1, v1
	v_fmamk_f32 v2, v2, 0xbfb8aa3b, v111
	v_fma_f32 v0, v0, v117, v117
	v_rcp_f32_e32 v0, v0
	v_fmamk_f32 v16, v16, 0xbfb8aa3b, v113
	v_fma_f32 v1, v1, v117, v117
	v_exp_f32_e32 v16, v16
	v_rcp_f32_e32 v1, v1
	v_fmamk_f32 v17, v17, 0xbfb8aa3b, v113
	v_add_f32_e32 v34, 1.0, v16
	v_exp_f32_e32 v16, v0
	v_exp_f32_e32 v17, v17
	v_exp_f32_e32 v1, v1
	v_rcp_f32_e32 v0, v34
	v_fma_f32 v34, -v16, v16, 1.0
	v_add_f32_e32 v17, 1.0, v17
	v_sqrt_f32_e32 v34, v34
	v_rcp_f32_e32 v35, v17
	v_fma_f32 v17, -v1, v1, 1.0
	v_sqrt_f32_e32 v101, v17
	v_exp_f32_e32 v2, v2
	v_fmamk_f32 v3, v3, 0xbfb8aa3b, v111
	ds_read_u16 v17, v100
	ds_read_u16 v102, v100 offset:144
	ds_read_u16 v103, v100 offset:288
	ds_read_u16 v119, v100 offset:432
	ds_read_u16 v121, v100 offset:1152
	ds_read_u16 v123, v100 offset:1296
	ds_read_u16 v125, v100 offset:1440
	ds_read_u16 v127, v100 offset:1584
	v_exp_f32_e32 v3, v3
	s_waitcnt lgkmcnt(7)
	v_lshlrev_b32_e32 v17, 16, v17
	v_mul_f32_e32 v0, v0, v34
	v_mul_f32_e32 v17, v0, v17
	v_mul_f32_e32 v0, v35, v101
	s_waitcnt lgkmcnt(6)
	v_lshlrev_b32_e32 v34, 16, v102
	v_fma_f32 v2, v2, v117, v117
	v_fmamk_f32 v18, v18, 0xbfb8aa3b, v113
	v_rcp_f32_e32 v101, v2
	v_mul_f32_e32 v2, v0, v34
	v_exp_f32_e32 v35, v18
	v_mul_f32_e32 v18, v1, v16
	v_fmac_f32_e32 v2, v1, v17
	v_fma_f32 v1, v3, v117, v117
	v_rcp_f32_e32 v1, v1
	v_fmamk_f32 v3, v19, 0xbfb8aa3b, v113
	v_add_f32_e32 v0, 1.0, v35
	v_exp_f32_e32 v35, v101
	v_exp_f32_e32 v3, v3
	v_exp_f32_e32 v1, v1
	v_fma_f32 v34, -v35, v35, 1.0
	v_add_f32_e32 v3, 1.0, v3
	v_rcp_f32_e32 v0, v0
	v_sqrt_f32_e32 v34, v34
	v_rcp_f32_e32 v101, v3
	v_fma_f32 v3, -v1, v1, 1.0
	v_sqrt_f32_e32 v102, v3
	v_mul_f32_e32 v0, v0, v34
	s_waitcnt lgkmcnt(5)
	v_lshlrev_b32_e32 v19, 16, v103
	v_mul_f32_e32 v3, v0, v19
	v_mul_f32_e32 v0, v101, v102
	s_waitcnt lgkmcnt(4)
	v_lshlrev_b32_e32 v19, 16, v119
	v_mul_f32_e32 v19, v0, v19
	v_fmamk_f32 v0, v4, 0xbfb8aa3b, v111
	v_exp_f32_e32 v0, v0
	v_fmamk_f32 v4, v20, 0xbfb8aa3b, v113
	v_exp_f32_e32 v4, v4
	v_mul_f32_e32 v34, v35, v18
	v_fmac_f32_e32 v3, v35, v2
	v_fma_f32 v0, v0, v117, v117
	v_mul_f32_e32 v35, v1, v34
	v_fmac_f32_e32 v19, v1, v3
	v_rcp_f32_e32 v0, v0
	v_add_f32_e32 v1, 1.0, v4
	v_fmamk_f32 v4, v5, 0xbfb8aa3b, v111
	v_exp_f32_e32 v5, v4
	v_exp_f32_e32 v4, v0
	v_rcp_f32_e32 v0, v1
	v_fma_f32 v1, v5, v117, v117
	v_rcp_f32_e32 v1, v1
	v_fmamk_f32 v20, v21, 0xbfb8aa3b, v113
	v_exp_f32_e32 v20, v20
	v_fma_f32 v5, -v4, v4, 1.0
	v_exp_f32_e32 v1, v1
	v_sqrt_f32_e32 v5, v5
	v_add_f32_e32 v20, 1.0, v20
	v_fmamk_f32 v6, v6, 0xbfb8aa3b, v111
	v_fma_f32 v21, -v1, v1, 1.0
	v_rcp_f32_e32 v20, v20
	v_sqrt_f32_e32 v21, v21
	v_exp_f32_e32 v6, v6
	v_fmamk_f32 v7, v7, 0xbfb8aa3b, v111
	v_exp_f32_e32 v7, v7
	s_waitcnt lgkmcnt(3)
	v_lshlrev_b32_e32 v101, 16, v121
	v_mul_f32_e32 v0, v0, v5
	v_mul_f32_e32 v5, v0, v101
	v_mul_f32_e32 v0, v20, v21
	s_waitcnt lgkmcnt(2)
	v_lshlrev_b32_e32 v20, 16, v123
	v_fmamk_f32 v21, v22, 0xbfb8aa3b, v113
	v_fma_f32 v6, v6, v117, v117
	v_exp_f32_e32 v21, v21
	v_rcp_f32_e32 v22, v6
	v_mul_f32_e32 v6, v0, v20
	v_mul_f32_e32 v20, v1, v4
	v_fmac_f32_e32 v6, v1, v5
	v_fma_f32 v1, v7, v117, v117
	v_rcp_f32_e32 v1, v1
	v_add_f32_e32 v0, 1.0, v21
	v_mov_b32_e32 v21, v22
	v_exp_f32_e32 v21, v21
	v_fmamk_f32 v7, v23, 0xbfb8aa3b, v113
	v_exp_f32_e32 v7, v7
	v_exp_f32_e32 v1, v1
	v_fma_f32 v22, -v21, v21, 1.0
	v_rcp_f32_e32 v0, v0
	v_sqrt_f32_e32 v22, v22
	v_add_f32_e32 v7, 1.0, v7
	v_rcp_f32_e32 v23, v7
	v_fma_f32 v7, -v1, v1, 1.0
	v_sqrt_f32_e32 v101, v7
	v_mul_f32_e32 v0, v0, v22
	s_waitcnt lgkmcnt(1)
	v_lshlrev_b32_e32 v22, 16, v125
	v_mul_f32_e32 v7, v0, v22
	v_mul_f32_e32 v22, v21, v20
	v_fmac_f32_e32 v7, v21, v6
	v_mul_f32_e32 v0, v23, v101
	s_waitcnt lgkmcnt(0)
	v_lshlrev_b32_e32 v21, 16, v127
	v_mul_f32_e32 v21, v0, v21
	v_fmamk_f32 v0, v8, 0xbfb8aa3b, v111
	v_exp_f32_e32 v0, v0
	v_fmamk_f32 v8, v24, 0xbfb8aa3b, v113
	v_exp_f32_e32 v8, v8
	v_mul_f32_e32 v23, v1, v22
	v_fma_f32 v0, v0, v117, v117
	v_fmac_f32_e32 v21, v1, v7
	v_rcp_f32_e32 v0, v0
	v_add_f32_e32 v1, 1.0, v8
	v_fmamk_f32 v8, v9, 0xbfb8aa3b, v111
	v_exp_f32_e32 v9, v8
	v_exp_f32_e32 v8, v0
	v_rcp_f32_e32 v0, v1
	v_fma_f32 v1, v9, v117, v117
	v_rcp_f32_e32 v1, v1
	v_fmamk_f32 v24, v25, 0xbfb8aa3b, v113
	v_exp_f32_e32 v24, v24
	v_fma_f32 v9, -v8, v8, 1.0
	v_exp_f32_e32 v1, v1
	v_sqrt_f32_e32 v9, v9
	v_add_f32_e32 v24, 1.0, v24
	v_fmamk_f32 v10, v10, 0xbfb8aa3b, v111
	v_fma_f32 v25, -v1, v1, 1.0
	v_rcp_f32_e32 v24, v24
	v_sqrt_f32_e32 v25, v25
	v_exp_f32_e32 v10, v10
	v_fmamk_f32 v11, v11, 0xbfb8aa3b, v111
	ds_read_u16 v101, v100 offset:2304
	ds_read_u16 v102, v100 offset:2448
	ds_read_u16 v103, v100 offset:2592
	ds_read_u16 v119, v100 offset:2736
	ds_read_u16 v121, v100 offset:3456
	ds_read_u16 v123, v100 offset:3600
	ds_read_u16 v125, v100 offset:3744
	ds_read_u16 v100, v100 offset:3888
	v_exp_f32_e32 v11, v11
	s_waitcnt lgkmcnt(7)
	v_lshlrev_b32_e32 v101, 16, v101
	v_mul_f32_e32 v0, v0, v9
	v_mul_f32_e32 v9, v0, v101
	v_mul_f32_e32 v0, v24, v25
	s_waitcnt lgkmcnt(6)
	v_lshlrev_b32_e32 v24, 16, v102
	v_fmamk_f32 v25, v26, 0xbfb8aa3b, v113
	v_fma_f32 v10, v10, v117, v117
	v_exp_f32_e32 v25, v25
	v_rcp_f32_e32 v26, v10
	v_mul_f32_e32 v10, v0, v24
	v_mul_f32_e32 v24, v1, v8
	v_fmac_f32_e32 v10, v1, v9
	v_fma_f32 v1, v11, v117, v117
	v_rcp_f32_e32 v1, v1
	v_add_f32_e32 v0, 1.0, v25
	v_mov_b32_e32 v25, v26
	v_exp_f32_e32 v25, v25
	v_fmamk_f32 v11, v27, 0xbfb8aa3b, v113
	v_exp_f32_e32 v11, v11
	v_exp_f32_e32 v1, v1
	v_fma_f32 v26, -v25, v25, 1.0
	v_rcp_f32_e32 v0, v0
	v_sqrt_f32_e32 v26, v26
	v_add_f32_e32 v11, 1.0, v11
	v_rcp_f32_e32 v27, v11
	v_fma_f32 v11, -v1, v1, 1.0
	v_sqrt_f32_e32 v101, v11
	v_mul_f32_e32 v0, v0, v26
	s_waitcnt lgkmcnt(5)
	v_lshlrev_b32_e32 v26, 16, v103
	v_mul_f32_e32 v11, v0, v26
	v_mul_f32_e32 v26, v25, v24
	v_fmac_f32_e32 v11, v25, v10
	v_mul_f32_e32 v0, v27, v101
	s_waitcnt lgkmcnt(4)
	v_lshlrev_b32_e32 v25, 16, v119
	v_mul_f32_e32 v25, v0, v25
	v_fmamk_f32 v0, v12, 0xbfb8aa3b, v111
	v_exp_f32_e32 v0, v0
	v_fmamk_f32 v12, v28, 0xbfb8aa3b, v113
	v_exp_f32_e32 v12, v12
	v_mul_f32_e32 v27, v1, v26
	v_fma_f32 v0, v0, v117, v117
	v_fmac_f32_e32 v25, v1, v11
	v_rcp_f32_e32 v0, v0
	v_add_f32_e32 v1, 1.0, v12
	v_fmamk_f32 v12, v13, 0xbfb8aa3b, v111
	v_exp_f32_e32 v13, v12
	v_exp_f32_e32 v12, v0
	v_rcp_f32_e32 v0, v1
	v_fma_f32 v1, v13, v117, v117
	v_rcp_f32_e32 v1, v1
	v_fmamk_f32 v28, v29, 0xbfb8aa3b, v113
	v_exp_f32_e32 v28, v28
	v_fma_f32 v13, -v12, v12, 1.0
	v_exp_f32_e32 v1, v1
	v_sqrt_f32_e32 v13, v13
	v_add_f32_e32 v28, 1.0, v28
	v_fmamk_f32 v14, v14, 0xbfb8aa3b, v111
	v_fma_f32 v29, -v1, v1, 1.0
	v_rcp_f32_e32 v28, v28
	v_sqrt_f32_e32 v29, v29
	v_exp_f32_e32 v14, v14
	v_fmamk_f32 v15, v15, 0xbfb8aa3b, v111
	v_exp_f32_e32 v15, v15
	s_waitcnt lgkmcnt(3)
	v_lshlrev_b32_e32 v101, 16, v121
	v_mul_f32_e32 v0, v0, v13
	v_mul_f32_e32 v13, v0, v101
	v_mul_f32_e32 v0, v28, v29
	s_waitcnt lgkmcnt(2)
	v_lshlrev_b32_e32 v28, 16, v123
	v_fmamk_f32 v29, v30, 0xbfb8aa3b, v113
	v_fma_f32 v14, v14, v117, v117
	v_exp_f32_e32 v29, v29
	v_rcp_f32_e32 v30, v14
	v_mul_f32_e32 v14, v0, v28
	v_mul_f32_e32 v28, v1, v12
	v_fmac_f32_e32 v14, v1, v13
	v_fma_f32 v1, v15, v117, v117
	v_rcp_f32_e32 v1, v1
	v_add_f32_e32 v0, 1.0, v29
	v_mov_b32_e32 v29, v30
	v_exp_f32_e32 v29, v29
	v_fmamk_f32 v15, v31, 0xbfb8aa3b, v113
	v_exp_f32_e32 v15, v15
	v_exp_f32_e32 v1, v1
	v_fma_f32 v30, -v29, v29, 1.0
	v_rcp_f32_e32 v0, v0
	v_sqrt_f32_e32 v30, v30
	v_add_f32_e32 v15, 1.0, v15
	v_rcp_f32_e32 v31, v15
	v_fma_f32 v15, -v1, v1, 1.0
	v_sqrt_f32_e32 v101, v15
	v_mul_f32_e32 v0, v0, v30
	s_waitcnt lgkmcnt(1)
	v_lshlrev_b32_e32 v30, 16, v125
	v_mul_f32_e32 v15, v0, v30
	v_mul_f32_e32 v30, v29, v28
	v_fmac_f32_e32 v15, v29, v14
	v_mul_f32_e32 v0, v31, v101
	s_waitcnt lgkmcnt(0)
	v_lshlrev_b32_e32 v29, 16, v100
	v_mul_f32_e32 v29, v0, v29
	ds_bpermute_b32 v100, v115, v35
	ds_bpermute_b32 v0, v115, v19
	ds_bpermute_b32 v119, v115, v23
	ds_bpermute_b32 v123, v115, v21
	ds_bpermute_b32 v131, v115, v27
	ds_bpermute_b32 v135, v115, v25
	v_mul_f32_e32 v31, v1, v30
	v_fmac_f32_e32 v29, v1, v15
	s_waitcnt lgkmcnt(5)
	v_cndmask_b32_e64 v103, v100, v35, s[4:5]
	s_waitcnt lgkmcnt(4)
	v_cndmask_b32_e64 v101, v0, v19, s[4:5]
	ds_bpermute_b32 v133, v115, v31
	ds_bpermute_b32 v1, v115, v29
	v_cndmask_b32_e64 v121, v35, v100, s[4:5]
	v_cndmask_b32_e64 v102, v19, v0, s[4:5]
	v_fmac_f32_e32 v101, 0, v103
	v_fmac_f32_e32 v102, v121, v101
	v_mul_f32_e32 v103, v35, v100
	s_waitcnt lgkmcnt(5)
	v_cndmask_b32_e64 v0, v119, v23, s[4:5]
	s_waitcnt lgkmcnt(4)
	v_cndmask_b32_e64 v121, v123, v21, s[4:5]
	v_cndmask_b32_e64 v119, v23, v119, s[4:5]
	v_cndmask_b32_e64 v123, v21, v123, s[4:5]
	v_fmac_f32_e32 v121, v0, v102
	v_mul_f32_e32 v125, v103, v0
	v_fmac_f32_e32 v123, v119, v121
	v_mul_f32_e32 v127, v119, v125
	s_waitcnt lgkmcnt(3)
	v_cndmask_b32_e64 v0, v131, v27, s[4:5]
	s_waitcnt lgkmcnt(2)
	v_cndmask_b32_e64 v129, v135, v25, s[4:5]
	v_cndmask_b32_e64 v119, v27, v131, s[4:5]
	v_cndmask_b32_e64 v131, v25, v135, s[4:5]
	v_fmac_f32_e32 v129, v0, v123
	v_mul_f32_e32 v135, v127, v0
	v_fmac_f32_e32 v131, v119, v129
	v_mul_f32_e32 v137, v119, v135
	s_waitcnt lgkmcnt(1)
	v_cndmask_b32_e64 v0, v133, v31, s[4:5]
	s_waitcnt lgkmcnt(0)
	v_cndmask_b32_e64 v139, v1, v29, s[4:5]
	v_fmac_f32_e32 v139, v0, v131
	v_mul_f32_e32 v141, v137, v0
	v_add_u32_e32 v119, s55, v186
	s_and_saveexec_b64 s[48:49], s[4:5]
	v_mul_f32_e32 v0, v141, v133
	v_fmac_f32_e32 v1, v133, v139
	ds_write_b64 v119, v[0:1] offset:36864
	s_or_b64 exec, exec, s[48:49]
	s_and_b64 s[14:15], s[12:13], exec
	s_cselect_b32 s16, s21, s23
	s_cselect_b32 s18, s20, s22
	s_lshl_b64 s[14:15], s[46:47], 21
	s_add_u32 s14, s18, s14
	s_addc_u32 s15, s16, s15
	s_add_u32 s14, s14, s0
	s_addc_u32 s15, s15, 0
	v_mov_b32_e32 v163, v32
	v_lshl_add_u64 v[166:167], s[14:15], 0, v[162:163]
	v_cndmask_b32_e64 v121, v121, v102, s[4:5]
	v_cndmask_b32_e64 v123, v129, v123, s[4:5]
	v_cndmask_b32_e64 v133, v101, 0, s[4:5]
	v_cndmask_b32_e64 v143, v100, 1.0, s[4:5]
	v_cndmask_b32_e64 v125, v125, v103, s[4:5]
	v_cndmask_b32_e64 v127, v135, v127, s[4:5]
	v_cndmask_b32_e64 v129, v139, v131, s[4:5]
	v_cndmask_b32_e64 v131, v141, v137, s[4:5]
	ds_read_b128 v[100:103], v176 offset:40960
	ds_read_b128 v[214:217], v176 offset:40976
	ds_read_b128 v[218:221], v176 offset:41216
	ds_read_b128 v[222:225], v176 offset:41232
	ds_read_b128 v[226:229], v176 offset:41472
	ds_read_b128 v[230:233], v176 offset:41488
	ds_read_b128 v[234:237], v176 offset:41984
	ds_read_b128 v[238:241], v176 offset:41728
	ds_read_b128 v[242:245], v176 offset:41744
	ds_read_b128 v[246:249], v176 offset:42000
	s_waitcnt vmcnt(7)
	v_lshlrev_b32_e32 v0, 16, v96
	v_and_b32_e32 v1, 0xffff0000, v96
	v_lshlrev_b32_e32 v96, 16, v97
	v_and_b32_e32 v97, 0xffff0000, v97
	s_waitcnt lgkmcnt(3)
	v_pk_fma_f32 v[0:1], v[100:101], v[0:1], v[234:235]
	s_waitcnt vmcnt(6)
	v_lshlrev_b32_e32 v172, 16, v92
	v_and_b32_e32 v173, 0xffff0000, v92
	v_pk_fma_f32 v[96:97], v[102:103], v[96:97], v[236:237]
	v_lshlrev_b32_e32 v92, 16, v93
	v_and_b32_e32 v93, 0xffff0000, v93
	v_pk_fma_f32 v[0:1], v[218:219], v[172:173], v[0:1]
	s_waitcnt vmcnt(5)
	v_lshlrev_b32_e32 v172, 16, v88
	v_and_b32_e32 v173, 0xffff0000, v88
	v_pk_fma_f32 v[92:93], v[220:221], v[92:93], v[96:97]
	v_lshlrev_b32_e32 v88, 16, v89
	v_and_b32_e32 v89, 0xffff0000, v89
	v_pk_fma_f32 v[0:1], v[226:227], v[172:173], v[0:1]
	s_waitcnt vmcnt(4)
	v_lshlrev_b32_e32 v172, 16, v84
	v_and_b32_e32 v173, 0xffff0000, v84
	v_pk_fma_f32 v[88:89], v[228:229], v[88:89], v[92:93]
	v_lshlrev_b32_e32 v84, 16, v85
	v_and_b32_e32 v85, 0xffff0000, v85
	s_waitcnt lgkmcnt(2)
	v_pk_fma_f32 v[88:89], v[240:241], v[84:85], v[88:89]
	v_lshlrev_b32_e32 v84, 16, v98
	v_and_b32_e32 v85, 0xffff0000, v98
	s_waitcnt lgkmcnt(0)
	v_pk_fma_f32 v[84:85], v[214:215], v[84:85], v[246:247]
	v_lshlrev_b32_e32 v92, 16, v94
	v_and_b32_e32 v93, 0xffff0000, v94
	v_pk_fma_f32 v[84:85], v[222:223], v[92:93], v[84:85]
	v_lshlrev_b32_e32 v92, 16, v90
	v_and_b32_e32 v93, 0xffff0000, v90
	v_pk_fma_f32 v[84:85], v[230:231], v[92:93], v[84:85]
	v_lshlrev_b32_e32 v92, 16, v86
	v_and_b32_e32 v93, 0xffff0000, v86
	v_pk_fma_f32 v[92:93], v[242:243], v[92:93], v[84:85]
	v_lshlrev_b32_e32 v84, 16, v99
	v_and_b32_e32 v85, 0xffff0000, v99
	v_pk_fma_f32 v[84:85], v[216:217], v[84:85], v[248:249]
	v_lshlrev_b32_e32 v94, 16, v95
	v_and_b32_e32 v95, 0xffff0000, v95
	v_pk_fma_f32 v[84:85], v[224:225], v[94:95], v[84:85]
	v_lshlrev_b32_e32 v90, 16, v91
	v_and_b32_e32 v91, 0xffff0000, v91
	v_pk_fma_f32 v[84:85], v[232:233], v[90:91], v[84:85]
	v_lshlrev_b32_e32 v86, 16, v87
	v_and_b32_e32 v87, 0xffff0000, v87
	v_pk_fma_f32 v[0:1], v[238:239], v[172:173], v[0:1]
	v_pk_fma_f32 v[90:91], v[244:245], v[86:87], v[84:85]
	v_cvt_pk_bf16_f32 v84, v0, v1
	v_cvt_pk_bf16_f32 v85, v88, v89
	v_cvt_pk_bf16_f32 v86, v92, v93
	v_cvt_pk_bf16_f32 v87, v90, v91
	s_waitcnt vmcnt(3)
	v_lshlrev_b32_e32 v0, 16, v80
	v_and_b32_e32 v1, 0xffff0000, v80
	v_lshlrev_b32_e32 v80, 16, v81
	v_and_b32_e32 v81, 0xffff0000, v81
	ds_write_b128 v33, v[84:87] offset:18432
	v_pk_fma_f32 v[0:1], v[100:101], v[0:1], v[234:235]
	s_waitcnt vmcnt(2)
	v_lshlrev_b32_e32 v84, 16, v76
	v_and_b32_e32 v85, 0xffff0000, v76
	v_pk_fma_f32 v[80:81], v[102:103], v[80:81], v[236:237]
	v_lshlrev_b32_e32 v76, 16, v77
	v_and_b32_e32 v77, 0xffff0000, v77
	v_pk_fma_f32 v[0:1], v[218:219], v[84:85], v[0:1]
	s_waitcnt vmcnt(1)
	v_lshlrev_b32_e32 v84, 16, v72
	v_and_b32_e32 v85, 0xffff0000, v72
	v_pk_fma_f32 v[76:77], v[220:221], v[76:77], v[80:81]
	v_lshlrev_b32_e32 v72, 16, v73
	v_and_b32_e32 v73, 0xffff0000, v73
	v_pk_fma_f32 v[0:1], v[226:227], v[84:85], v[0:1]
	s_waitcnt vmcnt(0)
	v_lshlrev_b32_e32 v84, 16, v68
	v_and_b32_e32 v85, 0xffff0000, v68
	v_pk_fma_f32 v[72:73], v[228:229], v[72:73], v[76:77]
	v_lshlrev_b32_e32 v68, 16, v69
	v_and_b32_e32 v69, 0xffff0000, v69
	v_pk_fma_f32 v[72:73], v[240:241], v[68:69], v[72:73]
	v_lshlrev_b32_e32 v68, 16, v82
	v_and_b32_e32 v69, 0xffff0000, v82
	v_pk_fma_f32 v[68:69], v[214:215], v[68:69], v[246:247]
	v_lshlrev_b32_e32 v76, 16, v78
	v_and_b32_e32 v77, 0xffff0000, v78
	v_pk_fma_f32 v[68:69], v[222:223], v[76:77], v[68:69]
	v_lshlrev_b32_e32 v76, 16, v74
	v_and_b32_e32 v77, 0xffff0000, v74
	v_pk_fma_f32 v[68:69], v[230:231], v[76:77], v[68:69]
	v_lshlrev_b32_e32 v76, 16, v70
	v_and_b32_e32 v77, 0xffff0000, v70
	v_pk_fma_f32 v[76:77], v[242:243], v[76:77], v[68:69]
	v_lshlrev_b32_e32 v68, 16, v83
	v_and_b32_e32 v69, 0xffff0000, v83
	v_pk_fma_f32 v[68:69], v[216:217], v[68:69], v[248:249]
	v_lshlrev_b32_e32 v78, 16, v79
	v_and_b32_e32 v79, 0xffff0000, v79
	v_pk_fma_f32 v[68:69], v[224:225], v[78:79], v[68:69]
	v_lshlrev_b32_e32 v74, 16, v75
	v_and_b32_e32 v75, 0xffff0000, v75
	v_pk_fma_f32 v[0:1], v[238:239], v[84:85], v[0:1]
	v_pk_fma_f32 v[68:69], v[232:233], v[74:75], v[68:69]
	v_lshlrev_b32_e32 v70, 16, v71
	v_and_b32_e32 v71, 0xffff0000, v71
	v_pk_fma_f32 v[74:75], v[244:245], v[70:71], v[68:69]
	v_cvt_pk_bf16_f32 v68, v0, v1
	v_cndmask_b32_e64 v0, v201, v187, s[12:13]
	v_mul_u32_u24_e32 v0, 0x700, v0
	v_cvt_pk_bf16_f32 v69, v72, v73
	v_cvt_pk_bf16_f32 v70, v76, v77
	v_cvt_pk_bf16_f32 v71, v74, v75
	v_lshlrev_b32_e32 v0, 1, v0
	v_mov_b32_e32 v1, v32
	ds_write_b128 v33, v[68:71] offset:27648
	v_lshl_add_u64 v[0:1], v[164:165], 0, v[0:1]
	v_lshl_add_u64 v[68:69], v[0:1], 0, s[40:41]
	global_load_dwordx4 v[76:79], v[0:1], off offset:-2048
	global_load_dwordx4 v[80:83], v[0:1], off offset:1536
	v_add_co_u32_e32 v0, vcc, s82, v0
	s_mov_b32 s0, 0
	s_nop 0
	v_addc_co_u32_e32 v1, vcc, 0, v1, vcc
	global_load_dwordx4 v[72:75], v[68:69], off offset:3584
	global_load_dwordx4 v[84:87], v[0:1], off offset:512
	v_cndmask_b32_e64 v0, v203, v202, s[12:13]
	v_mul_u32_u24_e32 v0, 0x700, v0
	v_lshlrev_b32_e32 v0, 1, v0
	v_mov_b32_e32 v1, v32
	v_lshl_add_u64 v[0:1], v[164:165], 0, v[0:1]
	v_lshl_add_u64 v[68:69], v[0:1], 0, s[40:41]
	global_load_dwordx4 v[88:91], v[0:1], off offset:-2048
	global_load_dwordx4 v[92:95], v[0:1], off offset:1536
	v_add_co_u32_e32 v0, vcc, s82, v0
	s_mov_b32 s14, 0
	s_nop 0
	v_addc_co_u32_e32 v1, vcc, 0, v1, vcc
	global_load_dwordx4 v[96:99], v[68:69], off offset:3584
	global_load_dwordx4 v[100:103], v[0:1], off offset:512
	s_waitcnt lgkmcnt(0)
	s_barrier
	ds_read2st64_b64 v[214:217], v204 offset0:72 offset1:73
	ds_read2st64_b64 v[68:71], v204 offset0:74 offset1:75
	s_mov_b32 s18, 0
	s_waitcnt lgkmcnt(1)
	v_fma_f32 v0, 0, v214, v215
	v_cndmask_b32_e64 v1, 0, v0, s[6:7]
	v_fmac_f32_e32 v217, v216, v0
	v_cndmask_b32_e64 v0, v1, v217, s[8:9]
	s_waitcnt lgkmcnt(0)
	v_fma_f32 v1, v68, v217, v69
	v_cndmask_b32_e64 v0, v0, v1, s[10:11]
	v_fmac_f32_e32 v133, v143, v0
	v_fmac_f32_e32 v17, v16, v133
	v_bfe_u32 v16, v17, 16, 1
	v_add3_u32 v16, v17, v16, s64
	v_fmac_f32_e32 v2, v18, v133
	ds_write_b16_d16_hi v195, v16 offset:42240
	v_bfe_u32 v16, v2, 16, 1
	v_add3_u32 v2, v2, v16, s64
	v_fmac_f32_e32 v3, v34, v133
	ds_write_b16_d16_hi v195, v2 offset:42368
	v_bfe_u32 v2, v3, 16, 1
	v_add3_u32 v2, v3, v2, s64
	v_fmac_f32_e32 v19, v35, v133
	ds_write_b16_d16_hi v195, v2 offset:42496
	v_bfe_u32 v2, v19, 16, 1
	v_fmac_f32_e32 v121, v125, v0
	v_add3_u32 v2, v19, v2, s64
	v_fmac_f32_e32 v5, v4, v121
	ds_write_b16_d16_hi v195, v2 offset:42624
	v_bfe_u32 v2, v5, 16, 1
	v_add3_u32 v2, v5, v2, s64
	v_fmac_f32_e32 v6, v20, v121
	ds_write_b16_d16_hi v195, v2 offset:43264
	v_bfe_u32 v2, v6, 16, 1
	v_add3_u32 v2, v6, v2, s64
	v_fmac_f32_e32 v7, v22, v121
	ds_write_b16_d16_hi v195, v2 offset:43392
	v_bfe_u32 v2, v7, 16, 1
	v_add3_u32 v2, v7, v2, s64
	v_fmac_f32_e32 v21, v23, v121
	ds_write_b16_d16_hi v195, v2 offset:43520
	v_bfe_u32 v2, v21, 16, 1
	v_fmac_f32_e32 v123, v127, v0
	v_fmac_f32_e32 v129, v131, v0
	v_add3_u32 v2, v21, v2, s64
	v_fmac_f32_e32 v9, v8, v123
	v_fmac_f32_e32 v13, v12, v129
	ds_write_b16_d16_hi v195, v2 offset:43648
	v_bfe_u32 v2, v9, 16, 1
	v_bfe_u32 v0, v13, 16, 1
	v_add3_u32 v2, v9, v2, s64
	v_fmac_f32_e32 v10, v24, v123
	v_add3_u32 v0, v13, v0, s64
	v_fmac_f32_e32 v14, v28, v129
	ds_write_b16_d16_hi v195, v2 offset:44288
	v_bfe_u32 v2, v10, 16, 1
	ds_write_b16_d16_hi v195, v0 offset:45312
	v_bfe_u32 v0, v14, 16, 1
	v_add3_u32 v2, v10, v2, s64
	v_fmac_f32_e32 v11, v26, v123
	v_add3_u32 v0, v14, v0, s64
	v_fmac_f32_e32 v15, v30, v129
	ds_write_b16_d16_hi v195, v2 offset:44416
	v_bfe_u32 v2, v11, 16, 1
	ds_write_b16_d16_hi v195, v0 offset:45440
	v_bfe_u32 v0, v15, 16, 1
	v_add3_u32 v2, v11, v2, s64
	v_fmac_f32_e32 v25, v27, v123
	v_add3_u32 v0, v15, v0, s64
	v_fmac_f32_e32 v29, v31, v129
	ds_write_b16_d16_hi v195, v2 offset:44544
	v_bfe_u32 v2, v25, 16, 1
	ds_write_b16_d16_hi v195, v0 offset:45568
	v_bfe_u32 v0, v29, 16, 1
	v_add3_u32 v2, v25, v2, s64
	v_add3_u32 v0, v29, v0, s64
	v_fmac_f32_e32 v71, v70, v1
	v_mov_b32_e32 v121, v192
	v_mov_b32_e32 v123, v170
	ds_write_b16_d16_hi v195, v2 offset:44672
	ds_write_b16_d16_hi v195, v0 offset:45696
.LBB0_317:
	s_add_i32 s15, s18, 1
	s_and_b32 s19, s15, 1
	s_mul_i32 s16, s19, 0x4800
	s_add_i32 s33, s16, 0
	v_add3_u32 v33, s33, v183, v184
	ds_read_b128 v[0:3], v33
	ds_read_b128 v[214:217], v33 offset:32
	s_lshl_b32 s19, s19, 14
	s_waitcnt lgkmcnt(1)
	v_mfma_f32_32x32x16_bf16 v[16:31], v[0:3], v[36:39], 0
	v_mfma_f32_32x32x16_bf16 v[0:15], v[0:3], v[40:43], 0
	s_waitcnt lgkmcnt(0)
	v_mfma_f32_32x32x16_bf16 v[16:31], v[214:217], v[44:47], v[16:31]
	v_mfma_f32_32x32x16_bf16 v[0:15], v[214:217], v[48:51], v[0:15]
	ds_read_b128 v[214:217], v33 offset:64
	ds_read_b128 v[218:221], v33 offset:96
	v_add3_u32 v33, s33, v185, v190
	ds_read_u16 v34, v33
	ds_read_u16 v35, v33 offset:144
	ds_read_u16 v68, v33 offset:288
	ds_read_u16 v69, v33 offset:432
	ds_read_u16 v70, v33 offset:1152
	ds_read_u16 v129, v33 offset:1296
	ds_read_u16 v131, v33 offset:1440
	ds_read_u16 v133, v33 offset:1584
	s_waitcnt lgkmcnt(7)
	v_lshlrev_b32_e32 v34, 16, v34
	s_waitcnt lgkmcnt(6)
	v_lshlrev_b32_e32 v35, 16, v35
	s_sub_i32 s33, s33, s19
	v_mfma_f32_32x32x16_bf16 v[16:31], v[214:217], v[52:55], v[16:31]
	v_mfma_f32_32x32x16_bf16 v[16:31], v[218:221], v[60:63], v[16:31]
	v_mfma_f32_32x32x16_bf16 v[0:15], v[214:217], v[56:59], v[0:15]
	s_nop 10
	v_fmamk_f32 v16, v16, 0xbfb8aa3b, v111
	v_fmamk_f32 v17, v17, 0xbfb8aa3b, v111
	v_exp_f32_e32 v16, v16
	v_exp_f32_e32 v17, v17
	v_fmamk_f32 v19, v19, 0xbfb8aa3b, v111
	v_fma_f32 v16, v16, v117, v117
	v_mfma_f32_32x32x16_bf16 v[0:15], v[218:221], v[64:67], v[0:15]
	v_fma_f32 v17, v17, v117, v117
	v_rcp_f32_e32 v16, v16
	v_rcp_f32_e32 v17, v17
	s_nop 6
	v_fmamk_f32 v0, v0, 0xbfb8aa3b, v113
	v_exp_f32_e32 v0, v0
	v_exp_f32_e32 v16, v16
	v_exp_f32_e32 v127, v17
	v_fmamk_f32 v17, v18, 0xbfb8aa3b, v111
	v_exp_f32_e32 v17, v17
	v_add_f32_e32 v0, 1.0, v0
	v_fma_f32 v125, -v16, v16, 1.0
	v_fmamk_f32 v2, v2, 0xbfb8aa3b, v113
	v_rcp_f32_e32 v0, v0
	v_sqrt_f32_e32 v125, v125
	v_exp_f32_e32 v2, v2
	v_fma_f32 v17, v17, v117, v117
	v_rcp_f32_e32 v17, v17
	v_fma_f32 v18, -v127, v127, 1.0
	v_add_f32_e32 v2, 1.0, v2
	v_mul_f32_e32 v0, v0, v125
	v_rcp_f32_e32 v135, v2
	v_mov_b32_e32 v2, v17
	v_sqrt_f32_e32 v17, v18
	v_mul_f32_e32 v18, v0, v34
	v_exp_f32_e32 v0, v19
	v_fmamk_f32 v1, v1, 0xbfb8aa3b, v113
	v_exp_f32_e32 v1, v1
	v_fmamk_f32 v3, v3, 0xbfb8aa3b, v113
	v_fma_f32 v0, v0, v117, v117
	v_rcp_f32_e32 v0, v0
	v_add_f32_e32 v1, 1.0, v1
	v_rcp_f32_e32 v1, v1
	v_exp_f32_e32 v137, v2
	v_exp_f32_e32 v3, v3
	v_exp_f32_e32 v0, v0
	v_mul_f32_e32 v1, v1, v17
	v_mul_f32_e32 v17, v1, v35
	v_fma_f32 v1, -v137, v137, 1.0
	v_add_f32_e32 v3, 1.0, v3
	v_sqrt_f32_e32 v1, v1
	v_rcp_f32_e32 v34, v3
	v_fma_f32 v3, -v0, v0, 1.0
	v_sqrt_f32_e32 v35, v3
	v_mul_f32_e32 v1, v135, v1
	s_waitcnt lgkmcnt(5)
	v_lshlrev_b32_e32 v19, 16, v68
	v_mul_f32_e32 v3, v1, v19
	v_mul_f32_e32 v1, v34, v35
	s_waitcnt lgkmcnt(4)
	v_lshlrev_b32_e32 v19, 16, v69
	v_mul_f32_e32 v19, v1, v19
	v_fmamk_f32 v1, v20, 0xbfb8aa3b, v111
	v_exp_f32_e32 v1, v1
	v_fmamk_f32 v4, v4, 0xbfb8aa3b, v113
	v_exp_f32_e32 v4, v4
	v_mul_f32_e32 v2, v127, v16
	v_fmac_f32_e32 v17, v127, v18
	v_mul_f32_e32 v125, v137, v2
	v_fmac_f32_e32 v3, v137, v17
	v_mul_f32_e32 v127, v0, v125
	v_fmac_f32_e32 v19, v0, v3
	v_fma_f32 v0, v1, v117, v117
	v_rcp_f32_e32 v0, v0
	v_add_f32_e32 v1, 1.0, v4
	v_fmamk_f32 v4, v21, 0xbfb8aa3b, v111
	v_exp_f32_e32 v20, v4
	v_exp_f32_e32 v4, v0
	v_rcp_f32_e32 v0, v1
	v_fma_f32 v1, v20, v117, v117
	v_rcp_f32_e32 v1, v1
	v_fmamk_f32 v5, v5, 0xbfb8aa3b, v113
	v_fma_f32 v20, -v4, v4, 1.0
	v_exp_f32_e32 v5, v5
	v_exp_f32_e32 v1, v1
	v_sqrt_f32_e32 v20, v20
	v_add_f32_e32 v5, 1.0, v5
	v_rcp_f32_e32 v21, v5
	v_fma_f32 v5, -v1, v1, 1.0
	v_mul_f32_e32 v0, v0, v20
	v_fmamk_f32 v20, v22, 0xbfb8aa3b, v111
	v_sqrt_f32_e32 v34, v5
	v_exp_f32_e32 v20, v20
	v_fmamk_f32 v6, v6, 0xbfb8aa3b, v113
	v_exp_f32_e32 v22, v6
	s_waitcnt lgkmcnt(3)
	v_lshlrev_b32_e32 v5, 16, v70
	v_mul_f32_e32 v5, v0, v5
	v_mul_f32_e32 v0, v21, v34
	s_waitcnt lgkmcnt(2)
	v_lshlrev_b32_e32 v21, 16, v129
	v_fma_f32 v6, v20, v117, v117
	v_rcp_f32_e32 v34, v6
	v_mul_f32_e32 v6, v0, v21
	v_add_f32_e32 v0, 1.0, v22
	v_fmamk_f32 v22, v23, 0xbfb8aa3b, v111
	v_exp_f32_e32 v22, v22
	v_mul_f32_e32 v20, v1, v4
	v_mov_b32_e32 v21, v34
	v_fmac_f32_e32 v6, v1, v5
	v_fma_f32 v1, v22, v117, v117
	v_exp_f32_e32 v21, v21
	v_rcp_f32_e32 v1, v1
	v_fmamk_f32 v7, v7, 0xbfb8aa3b, v113
	v_exp_f32_e32 v7, v7
	v_fma_f32 v23, -v21, v21, 1.0
	v_rcp_f32_e32 v0, v0
	v_sqrt_f32_e32 v23, v23
	v_exp_f32_e32 v1, v1
	v_add_f32_e32 v7, 1.0, v7
	s_waitcnt lgkmcnt(1)
	v_lshlrev_b32_e32 v22, 16, v131
	v_mul_f32_e32 v0, v0, v23
	v_rcp_f32_e32 v23, v7
	v_fma_f32 v7, -v1, v1, 1.0
	v_sqrt_f32_e32 v34, v7
	v_mul_f32_e32 v7, v0, v22
	v_mul_f32_e32 v22, v21, v20
	v_fmac_f32_e32 v7, v21, v6
	v_mul_f32_e32 v0, v23, v34
	s_waitcnt lgkmcnt(0)
	v_lshlrev_b32_e32 v21, 16, v133
	v_mul_f32_e32 v21, v0, v21
	v_fmamk_f32 v0, v24, 0xbfb8aa3b, v111
	v_exp_f32_e32 v0, v0
	v_fmamk_f32 v8, v8, 0xbfb8aa3b, v113
	v_exp_f32_e32 v8, v8
	v_mul_f32_e32 v23, v1, v22
	v_fma_f32 v0, v0, v117, v117
	v_fmac_f32_e32 v21, v1, v7
	v_rcp_f32_e32 v0, v0
	v_add_f32_e32 v1, 1.0, v8
	v_fmamk_f32 v8, v25, 0xbfb8aa3b, v111
	v_exp_f32_e32 v24, v8
	v_exp_f32_e32 v8, v0
	v_rcp_f32_e32 v0, v1
	v_fma_f32 v1, v24, v117, v117
	v_rcp_f32_e32 v1, v1
	v_fmamk_f32 v9, v9, 0xbfb8aa3b, v113
	v_fma_f32 v24, -v8, v8, 1.0
	v_exp_f32_e32 v9, v9
	v_exp_f32_e32 v1, v1
	v_sqrt_f32_e32 v24, v24
	v_add_f32_e32 v9, 1.0, v9
	v_rcp_f32_e32 v25, v9
	v_fma_f32 v9, -v1, v1, 1.0
	v_mul_f32_e32 v0, v0, v24
	v_fmamk_f32 v24, v26, 0xbfb8aa3b, v111
	v_sqrt_f32_e32 v34, v9
	v_exp_f32_e32 v24, v24
	v_fmamk_f32 v10, v10, 0xbfb8aa3b, v113
	v_exp_f32_e32 v26, v10
	ds_read_u16 v9, v33 offset:2304
	ds_read_u16 v35, v33 offset:2448
	ds_read_u16 v68, v33 offset:2592
	ds_read_u16 v69, v33 offset:2736
	ds_read_u16 v70, v33 offset:3456
	ds_read_u16 v129, v33 offset:3600
	ds_read_u16 v131, v33 offset:3744
	ds_read_u16 v33, v33 offset:3888
	s_waitcnt lgkmcnt(7)
	v_lshlrev_b32_e32 v9, 16, v9
	v_mul_f32_e32 v9, v0, v9
	v_mul_f32_e32 v0, v25, v34
	s_waitcnt lgkmcnt(6)
	v_lshlrev_b32_e32 v25, 16, v35
	v_fma_f32 v10, v24, v117, v117
	v_rcp_f32_e32 v34, v10
	v_mul_f32_e32 v10, v0, v25
	v_add_f32_e32 v0, 1.0, v26
	v_fmamk_f32 v26, v27, 0xbfb8aa3b, v111
	v_exp_f32_e32 v26, v26
	v_mul_f32_e32 v24, v1, v8
	v_mov_b32_e32 v25, v34
	v_fmac_f32_e32 v10, v1, v9
	v_fma_f32 v1, v26, v117, v117
	v_exp_f32_e32 v25, v25
	v_rcp_f32_e32 v1, v1
	v_fmamk_f32 v11, v11, 0xbfb8aa3b, v113
	v_exp_f32_e32 v11, v11
	v_fma_f32 v27, -v25, v25, 1.0
	v_rcp_f32_e32 v0, v0
	v_sqrt_f32_e32 v27, v27
	v_exp_f32_e32 v1, v1
	v_add_f32_e32 v11, 1.0, v11
	s_waitcnt lgkmcnt(5)
	v_lshlrev_b32_e32 v26, 16, v68
	v_mul_f32_e32 v0, v0, v27
	v_rcp_f32_e32 v27, v11
	v_fma_f32 v11, -v1, v1, 1.0
	v_sqrt_f32_e32 v34, v11
	v_mul_f32_e32 v11, v0, v26
	v_mul_f32_e32 v26, v25, v24
	v_fmac_f32_e32 v11, v25, v10
	v_mul_f32_e32 v0, v27, v34
	s_waitcnt lgkmcnt(4)
	v_lshlrev_b32_e32 v25, 16, v69
	v_mul_f32_e32 v25, v0, v25
	v_fmamk_f32 v0, v28, 0xbfb8aa3b, v111
	v_exp_f32_e32 v0, v0
	v_fmamk_f32 v12, v12, 0xbfb8aa3b, v113
	v_exp_f32_e32 v12, v12
	v_mul_f32_e32 v27, v1, v26
	v_fma_f32 v0, v0, v117, v117
	v_fmac_f32_e32 v25, v1, v11
	v_rcp_f32_e32 v0, v0
	v_add_f32_e32 v1, 1.0, v12
	v_fmamk_f32 v12, v29, 0xbfb8aa3b, v111
	v_exp_f32_e32 v28, v12
	v_exp_f32_e32 v12, v0
	v_rcp_f32_e32 v0, v1
	v_fma_f32 v1, v28, v117, v117
	v_rcp_f32_e32 v1, v1
	v_fmamk_f32 v13, v13, 0xbfb8aa3b, v113
	v_fma_f32 v28, -v12, v12, 1.0
	v_exp_f32_e32 v13, v13
	v_exp_f32_e32 v1, v1
	v_sqrt_f32_e32 v28, v28
	v_add_f32_e32 v13, 1.0, v13
	v_rcp_f32_e32 v29, v13
	v_fma_f32 v13, -v1, v1, 1.0
	v_mul_f32_e32 v0, v0, v28
	v_fmamk_f32 v28, v30, 0xbfb8aa3b, v111
	v_sqrt_f32_e32 v34, v13
	v_exp_f32_e32 v28, v28
	v_fmamk_f32 v14, v14, 0xbfb8aa3b, v113
	v_exp_f32_e32 v30, v14
	s_waitcnt lgkmcnt(3)
	v_lshlrev_b32_e32 v13, 16, v70
	v_mul_f32_e32 v13, v0, v13
	v_mul_f32_e32 v0, v29, v34
	s_waitcnt lgkmcnt(2)
	v_lshlrev_b32_e32 v29, 16, v129
	v_fma_f32 v14, v28, v117, v117
	v_rcp_f32_e32 v34, v14
	v_mul_f32_e32 v14, v0, v29
	v_add_f32_e32 v0, 1.0, v30
	v_fmamk_f32 v30, v31, 0xbfb8aa3b, v111
	v_exp_f32_e32 v30, v30
	v_mul_f32_e32 v28, v1, v12
	v_mov_b32_e32 v29, v34
	v_fmac_f32_e32 v14, v1, v13
	v_fma_f32 v1, v30, v117, v117
	v_exp_f32_e32 v29, v29
	v_rcp_f32_e32 v1, v1
	v_fmamk_f32 v15, v15, 0xbfb8aa3b, v113
	v_exp_f32_e32 v15, v15
	v_fma_f32 v31, -v29, v29, 1.0
	v_rcp_f32_e32 v0, v0
	v_sqrt_f32_e32 v31, v31
	v_exp_f32_e32 v1, v1
	v_add_f32_e32 v15, 1.0, v15
	s_waitcnt lgkmcnt(1)
	v_lshlrev_b32_e32 v30, 16, v131
	v_mul_f32_e32 v0, v0, v31
	v_rcp_f32_e32 v31, v15
	v_fma_f32 v15, -v1, v1, 1.0
	v_sqrt_f32_e32 v34, v15
	v_mul_f32_e32 v15, v0, v30
	v_mul_f32_e32 v30, v29, v28
	v_fmac_f32_e32 v15, v29, v14
	v_mul_f32_e32 v0, v31, v34
	s_waitcnt lgkmcnt(0)
	v_lshlrev_b32_e32 v29, 16, v33
	v_mul_f32_e32 v29, v0, v29
	ds_bpermute_b32 v68, v115, v127
	ds_bpermute_b32 v0, v115, v19
	ds_bpermute_b32 v34, v115, v23
	ds_bpermute_b32 v35, v115, v21
	ds_bpermute_b32 v141, v115, v27
	ds_bpermute_b32 v143, v115, v25
	v_mul_f32_e32 v31, v1, v30
	v_fmac_f32_e32 v29, v1, v15
	s_waitcnt lgkmcnt(5)
	v_cndmask_b32_e64 v129, v68, v127, s[4:5]
	s_waitcnt lgkmcnt(4)
	v_cndmask_b32_e64 v69, v0, v19, s[4:5]
	ds_bpermute_b32 v33, v115, v31
	ds_bpermute_b32 v1, v115, v29
	v_cndmask_b32_e64 v131, v127, v68, s[4:5]
	v_cndmask_b32_e64 v70, v19, v0, s[4:5]
	v_fmac_f32_e32 v69, 0, v129
	v_fmac_f32_e32 v70, v131, v69
	v_mul_f32_e32 v129, v127, v68
	s_waitcnt lgkmcnt(5)
	v_cndmask_b32_e64 v0, v34, v23, s[4:5]
	s_waitcnt lgkmcnt(4)
	v_cndmask_b32_e64 v131, v35, v21, s[4:5]
	v_cndmask_b32_e64 v34, v23, v34, s[4:5]
	v_cndmask_b32_e64 v133, v21, v35, s[4:5]
	v_fmac_f32_e32 v131, v0, v70
	v_mul_f32_e32 v135, v129, v0
	v_fmac_f32_e32 v133, v34, v131
	v_mul_f32_e32 v137, v34, v135
	s_waitcnt lgkmcnt(3)
	v_cndmask_b32_e64 v0, v141, v27, s[4:5]
	s_waitcnt lgkmcnt(2)
	v_cndmask_b32_e64 v139, v143, v25, s[4:5]
	v_cndmask_b32_e64 v34, v27, v141, s[4:5]
	v_cndmask_b32_e64 v141, v25, v143, s[4:5]
	v_fmac_f32_e32 v139, v0, v133
	v_mul_f32_e32 v143, v137, v0
	v_fmac_f32_e32 v141, v34, v139
	v_mul_f32_e32 v145, v34, v143
	s_waitcnt lgkmcnt(1)
	v_cndmask_b32_e64 v0, v33, v31, s[4:5]
	s_waitcnt lgkmcnt(0)
	v_cndmask_b32_e64 v147, v1, v29, s[4:5]
	v_fmac_f32_e32 v147, v0, v141
	v_mul_f32_e32 v149, v145, v0
	s_and_saveexec_b64 s[46:47], s[4:5]
	s_add_i32 s16, s33, s54
	v_mul_f32_e32 v0, v149, v33
	v_fmac_f32_e32 v1, v33, v147
	v_add_u32_e32 v33, s16, v186
	ds_write_b64 v33, v[0:1] offset:36864
	s_or_b64 exec, exec, s[46:47]
	ds_read_b128 v[214:217], v176 offset:40960
	ds_read_b128 v[218:221], v176 offset:40976
	ds_read_b128 v[222:225], v176 offset:41216
	ds_read_b128 v[226:229], v176 offset:41232
	ds_read_b128 v[230:233], v176 offset:41472
	ds_read_b128 v[234:237], v176 offset:41488
	ds_read_b128 v[238:241], v176 offset:41728
	ds_read_b128 v[242:245], v176 offset:41744
	ds_read_b128 v[246:249], v176 offset:41984
	ds_read_b128 v[250:253], v176 offset:42000
	s_waitcnt vmcnt(3)
	v_lshlrev_b32_e32 v0, 16, v76
	v_and_b32_e32 v1, 0xffff0000, v76
	s_waitcnt vmcnt(2)
	v_lshlrev_b32_e32 v34, 16, v80
	s_waitcnt lgkmcnt(1)
	v_pk_fma_f32 v[0:1], v[214:215], v[0:1], v[246:247]
	v_and_b32_e32 v35, 0xffff0000, v80
	v_pk_fma_f32 v[0:1], v[222:223], v[34:35], v[0:1]
	s_waitcnt vmcnt(5)
	v_lshlrev_b32_e32 v34, 16, v72
	v_and_b32_e32 v35, 0xffff0000, v72
	v_pk_fma_f32 v[0:1], v[230:231], v[34:35], v[0:1]
	s_waitcnt vmcnt(4)
	v_lshlrev_b32_e32 v34, 16, v84
	v_and_b32_e32 v35, 0xffff0000, v84
	v_pk_fma_f32 v[0:1], v[238:239], v[34:35], v[0:1]
	v_lshlrev_b32_e32 v34, 16, v77
	v_and_b32_e32 v35, 0xffff0000, v77
	v_pk_fma_f32 v[34:35], v[216:217], v[34:35], v[248:249]
	v_lshlrev_b32_e32 v172, 16, v81
	v_and_b32_e32 v173, 0xffff0000, v81
	v_pk_fma_f32 v[34:35], v[224:225], v[172:173], v[34:35]
	v_lshlrev_b32_e32 v172, 16, v73
	v_and_b32_e32 v173, 0xffff0000, v73
	v_pk_fma_f32 v[34:35], v[232:233], v[172:173], v[34:35]
	v_lshlrev_b32_e32 v172, 16, v85
	v_and_b32_e32 v173, 0xffff0000, v85
	v_pk_fma_f32 v[34:35], v[240:241], v[172:173], v[34:35]
	v_lshlrev_b32_e32 v172, 16, v78
	v_and_b32_e32 v173, 0xffff0000, v78
	s_waitcnt lgkmcnt(0)
	v_pk_fma_f32 v[172:173], v[218:219], v[172:173], v[250:251]
	v_lshlrev_b32_e32 v174, 16, v82
	v_and_b32_e32 v175, 0xffff0000, v82
	v_pk_fma_f32 v[172:173], v[226:227], v[174:175], v[172:173]
	v_lshlrev_b32_e32 v174, 16, v74
	v_and_b32_e32 v175, 0xffff0000, v74
	v_pk_fma_f32 v[172:173], v[234:235], v[174:175], v[172:173]
	v_lshlrev_b32_e32 v174, 16, v86
	v_and_b32_e32 v175, 0xffff0000, v86
	v_pk_fma_f32 v[174:175], v[242:243], v[174:175], v[172:173]
	v_lshlrev_b32_e32 v172, 16, v79
	v_and_b32_e32 v173, 0xffff0000, v79
	v_pk_fma_f32 v[172:173], v[220:221], v[172:173], v[252:253]
	v_lshlrev_b32_e32 v180, 16, v83
	v_and_b32_e32 v181, 0xffff0000, v83
	v_pk_fma_f32 v[172:173], v[228:229], v[180:181], v[172:173]
	v_lshlrev_b32_e32 v180, 16, v75
	v_and_b32_e32 v181, 0xffff0000, v75
	v_pk_fma_f32 v[172:173], v[236:237], v[180:181], v[172:173]
	v_lshlrev_b32_e32 v180, 16, v87
	v_and_b32_e32 v181, 0xffff0000, v87
	v_pk_fma_f32 v[180:181], v[244:245], v[180:181], v[172:173]
	v_cvt_pk_bf16_f32 v172, v0, v1
	s_waitcnt vmcnt(3)
	v_lshlrev_b32_e32 v0, 16, v88
	v_and_b32_e32 v1, 0xffff0000, v88
	v_cvt_pk_bf16_f32 v173, v34, v35
	v_pk_fma_f32 v[0:1], v[214:215], v[0:1], v[246:247]
	s_waitcnt vmcnt(2)
	v_lshlrev_b32_e32 v34, 16, v92
	v_and_b32_e32 v35, 0xffff0000, v92
	s_bitcmp1_b32 s18, 0
	v_pk_fma_f32 v[0:1], v[222:223], v[34:35], v[0:1]
	s_waitcnt vmcnt(1)
	v_lshlrev_b32_e32 v34, 16, v96
	v_and_b32_e32 v35, 0xffff0000, v96
	s_cselect_b32 s16, 0x4800, 0
	v_pk_fma_f32 v[0:1], v[230:231], v[34:35], v[0:1]
	s_waitcnt vmcnt(0)
	v_lshlrev_b32_e32 v34, 16, v100
	v_and_b32_e32 v35, 0xffff0000, v100
	v_cvt_pk_bf16_f32 v174, v174, v175
	v_cvt_pk_bf16_f32 v175, v180, v181
	v_add3_u32 v33, v177, s16, v178
	v_pk_fma_f32 v[0:1], v[238:239], v[34:35], v[0:1]
	v_lshlrev_b32_e32 v34, 16, v89
	v_and_b32_e32 v35, 0xffff0000, v89
	ds_write_b128 v33, v[172:175]
	v_pk_fma_f32 v[34:35], v[216:217], v[34:35], v[248:249]
	v_lshlrev_b32_e32 v172, 16, v93
	v_and_b32_e32 v173, 0xffff0000, v93
	v_pk_fma_f32 v[34:35], v[224:225], v[172:173], v[34:35]
	v_lshlrev_b32_e32 v172, 16, v97
	v_and_b32_e32 v173, 0xffff0000, v97
	v_pk_fma_f32 v[34:35], v[232:233], v[172:173], v[34:35]
	v_lshlrev_b32_e32 v172, 16, v101
	v_and_b32_e32 v173, 0xffff0000, v101
	v_pk_fma_f32 v[34:35], v[240:241], v[172:173], v[34:35]
	v_lshlrev_b32_e32 v172, 16, v90
	v_and_b32_e32 v173, 0xffff0000, v90
	v_pk_fma_f32 v[172:173], v[218:219], v[172:173], v[250:251]
	v_lshlrev_b32_e32 v174, 16, v94
	v_and_b32_e32 v175, 0xffff0000, v94
	v_pk_fma_f32 v[172:173], v[226:227], v[174:175], v[172:173]
	v_lshlrev_b32_e32 v174, 16, v98
	v_and_b32_e32 v175, 0xffff0000, v98
	v_pk_fma_f32 v[172:173], v[234:235], v[174:175], v[172:173]
	v_lshlrev_b32_e32 v174, 16, v102
	v_and_b32_e32 v175, 0xffff0000, v102
	v_pk_fma_f32 v[174:175], v[242:243], v[174:175], v[172:173]
	v_lshlrev_b32_e32 v172, 16, v91
	v_and_b32_e32 v173, 0xffff0000, v91
	v_pk_fma_f32 v[172:173], v[220:221], v[172:173], v[252:253]
	v_lshlrev_b32_e32 v180, 16, v95
	v_and_b32_e32 v181, 0xffff0000, v95
	v_pk_fma_f32 v[172:173], v[228:229], v[180:181], v[172:173]
	v_lshlrev_b32_e32 v180, 16, v99
	v_and_b32_e32 v181, 0xffff0000, v99
	v_pk_fma_f32 v[172:173], v[236:237], v[180:181], v[172:173]
	v_lshlrev_b32_e32 v180, 16, v103
	v_and_b32_e32 v181, 0xffff0000, v103
	v_pk_fma_f32 v[180:181], v[244:245], v[180:181], v[172:173]
	v_cvt_pk_bf16_f32 v172, v0, v1
	v_cvt_pk_bf16_f32 v173, v34, v35
	v_cvt_pk_bf16_f32 v174, v174, v175
	v_cvt_pk_bf16_f32 v175, v180, v181
	s_mov_b64 s[46:47], -1
	s_cmp_lt_u32 s15, 14
	v_add_u32_e32 v151, s14, v206
	ds_write_b128 v33, v[172:175] offset:9216
	s_cbranch_scc1 .LBB0_321
	v_add_u32_e32 v0, s14, v206
	s_mov_b64 s[46:47], 0
.LBB0_321:
	s_andn2_b64 vcc, exec, s[46:47]
	s_cbranch_vccnz .LBB0_337
	v_add_u32_e32 v0, 0x180, v123
	v_add_u32_e32 v1, 0x67f, v151
	v_cndmask_b32_e64 v33, v1, v0, s[12:13]
	v_mov_b32_e32 v74, v32
	v_mov_b32_e32 v75, v32
	v_add_u32_e32 v0, -1, v33
	v_mov_b32_e32 v72, v32
	v_mov_b32_e32 v73, v32
	v_mov_b64_e32 v[78:79], v[74:75]
	v_cmp_gt_u32_e32 vcc, s50, v0
	v_mov_b64_e32 v[76:77], v[72:73]
	s_and_saveexec_b64 s[46:47], vcc
	s_cbranch_execz .LBB0_324
	v_mul_u32_u24_e32 v0, s60, v0
	v_mov_b32_e32 v1, v32
	v_lshl_add_u64 v[0:1], v[0:1], 1, v[164:165]
	global_load_dwordx4 v[76:79], v[0:1], off offset:1536
.LBB0_324:
	s_or_b64 exec, exec, s[46:47]
	v_mul_u32_u24_e32 v0, s60, v33
	v_mov_b32_e32 v1, v32
	v_lshl_add_u64 v[0:1], v[0:1], 1, v[164:165]
	global_load_dwordx4 v[80:83], v[0:1], off offset:1536
	v_lshl_add_u64 v[0:1], v[0:1], 0, s[40:41]
	v_cmp_gt_u32_e32 vcc, s51, v33
	s_and_saveexec_b64 s[46:47], vcc
	s_cbranch_execz .LBB0_326
	global_load_dwordx4 v[72:75], v[0:1], off offset:3584

.LBB0_328:
	s_or_b64 exec, exec, s[46:47]
	v_add_u32_e32 v0, 0x1c0, v123
	v_add_u32_e32 v1, 0x63f, v151
	v_cndmask_b32_e64 v0, v1, v0, s[12:13]
	v_add_u32_e32 v1, -1, v0
	v_mov_b64_e32 v[90:91], v[34:35]
	v_cmp_gt_u32_e32 vcc, s50, v1
	v_mov_b64_e32 v[88:89], v[32:33]
	s_and_saveexec_b64 s[46:47], vcc
	s_cbranch_execz .LBB0_330
	v_mul_u32_u24_e32 v34, s60, v1
	v_mov_b32_e32 v35, v32
	v_lshl_add_u64 v[34:35], v[34:35], 1, v[164:165]
	global_load_dwordx4 v[88:91], v[34:35], off offset:1536
.LBB0_330:
	s_or_b64 exec, exec, s[46:47]
	v_mov_b32_e32 v34, v32
	v_mov_b32_e32 v35, v32
	v_mov_b32_e32 v33, v32
	v_mov_b64_e32 v[94:95], v[34:35]
	v_cmp_gt_u32_e32 vcc, s50, v0
	v_mov_b64_e32 v[92:93], v[32:33]
	s_and_saveexec_b64 s[46:47], vcc
	s_cbranch_execz .LBB0_332
	v_mul_u32_u24_e32 v92, s60, v0
	v_mov_b32_e32 v93, v32
	v_lshl_add_u64 v[92:93], v[92:93], 1, v[164:165]
	global_load_dwordx4 v[92:95], v[92:93], off offset:1536
.LBB0_332:
	s_or_b64 exec, exec, s[46:47]
	v_add_u32_e32 v1, 1, v0
	v_mov_b64_e32 v[98:99], v[34:35]
	v_cmp_gt_u32_e32 vcc, s50, v1
	v_mov_b64_e32 v[96:97], v[32:33]
	s_and_saveexec_b64 s[46:47], vcc
	s_cbranch_execz .LBB0_334
	v_mul_u32_u24_e32 v34, s60, v1
	v_mov_b32_e32 v35, v32
	v_lshl_add_u64 v[34:35], v[34:35], 1, v[164:165]
	global_load_dwordx4 v[96:99], v[34:35], off offset:1536
.LBB0_334:
	s_or_b64 exec, exec, s[46:47]
	v_mov_b32_e32 v34, v32
	v_mov_b32_e32 v35, v32
	v_add_u32_e32 v0, 2, v0
	v_mov_b32_e32 v33, v32
	v_mov_b64_e32 v[102:103], v[34:35]
	v_cmp_gt_u32_e32 vcc, s50, v0
	v_mov_b64_e32 v[100:101], v[32:33]
	s_and_saveexec_b64 s[46:47], vcc
	s_cbranch_execz .LBB0_336
	v_mul_u32_u24_e32 v0, s60, v0
	v_mov_b32_e32 v1, v32
	v_lshl_add_u64 v[0:1], v[0:1], 1, v[164:165]
	global_load_dwordx4 v[100:103], v[0:1], off offset:1536

.LBB0_339:
	ds_read_b128 v[0:3], v213 offset:18432
	s_waitcnt vmcnt(2)
	ds_read_b128 v[72:75], v213 offset:18464
	s_waitcnt lgkmcnt(1)
	v_mfma_f32_32x32x16_bf16 v[16:31], v[0:3], v[36:39], 0
	s_waitcnt lgkmcnt(0)
	v_mfma_f32_32x32x16_bf16 v[16:31], v[72:75], v[44:47], v[16:31]
	v_mfma_f32_32x32x16_bf16 v[0:15], v[0:3], v[40:43], 0
	ds_read_b128 v[34:37], v213 offset:18496
	ds_read_b128 v[38:41], v213 offset:18528
	s_waitcnt lgkmcnt(1)
	v_mfma_f32_32x32x16_bf16 v[16:31], v[34:37], v[52:55], v[16:31]
	v_mfma_f32_32x32x16_bf16 v[0:15], v[72:75], v[48:51], v[0:15]
	s_waitcnt lgkmcnt(0)
	v_mfma_f32_32x32x16_bf16 v[16:31], v[38:41], v[60:63], v[16:31]
	v_mfma_f32_32x32x16_bf16 v[0:15], v[34:37], v[56:59], v[0:15]
	s_nop 10
	v_fmamk_f32 v16, v16, 0xbfb8aa3b, v111
	v_exp_f32_e32 v16, v16
	v_fmamk_f32 v17, v17, 0xbfb8aa3b, v111
	v_exp_f32_e32 v17, v17
	v_add_u32_e32 v35, v205, v190
	v_fma_f32 v16, v16, v117, v117
	v_rcp_f32_e32 v16, v16
	v_mfma_f32_32x32x16_bf16 v[0:15], v[38:41], v[64:67], v[0:15]
	v_fma_f32 v17, v17, v117, v117
	v_rcp_f32_e32 v17, v17
	v_exp_f32_e32 v16, v16
	ds_read_u16 v36, v35 offset:18432
	ds_read_u16 v37, v35 offset:18576
	ds_read_u16 v38, v35 offset:18720
	ds_read_u16 v39, v35 offset:18864
	ds_read_u16 v40, v35 offset:19584
	ds_read_u16 v41, v35 offset:19728
	ds_read_u16 v42, v35 offset:19872
	ds_read_u16 v43, v35 offset:20016
	v_exp_f32_e32 v34, v17
	v_fmamk_f32 v0, v0, 0xbfb8aa3b, v113
	v_exp_f32_e32 v0, v0
	v_fmamk_f32 v1, v1, 0xbfb8aa3b, v113
	v_exp_f32_e32 v1, v1
	v_fma_f32 v33, -v16, v16, 1.0
	v_add_f32_e32 v0, 1.0, v0
	v_rcp_f32_e32 v0, v0
	v_sqrt_f32_e32 v17, v33
	v_add_f32_e32 v1, 1.0, v1
	v_fma_f32 v33, -v34, v34, 1.0
	v_rcp_f32_e32 v1, v1
	v_sqrt_f32_e32 v33, v33
	s_waitcnt lgkmcnt(7)
	v_lshlrev_b32_e32 v36, 16, v36
	v_mul_f32_e32 v0, v0, v17
	v_mul_f32_e32 v17, v0, v36
	v_mul_f32_e32 v0, v1, v33
	v_fmamk_f32 v1, v18, 0xbfb8aa3b, v111
	v_exp_f32_e32 v1, v1
	v_fmamk_f32 v19, v19, 0xbfb8aa3b, v111
	v_exp_f32_e32 v19, v19
	v_fmamk_f32 v2, v2, 0xbfb8aa3b, v113
	v_fma_f32 v1, v1, v117, v117
	v_rcp_f32_e32 v1, v1
	v_fma_f32 v19, v19, v117, v117
	v_rcp_f32_e32 v19, v19
	v_exp_f32_e32 v33, v2
	v_exp_f32_e32 v1, v1
	v_fmamk_f32 v3, v3, 0xbfb8aa3b, v113
	v_exp_f32_e32 v3, v3
	v_exp_f32_e32 v36, v19
	s_waitcnt lgkmcnt(6)
	v_lshlrev_b32_e32 v18, 16, v37
	v_mul_f32_e32 v2, v0, v18
	v_add_f32_e32 v0, 1.0, v33
	v_fma_f32 v33, -v1, v1, 1.0
	v_rcp_f32_e32 v0, v0
	v_sqrt_f32_e32 v33, v33
	v_add_f32_e32 v3, 1.0, v3
	v_mul_f32_e32 v18, v34, v16
	v_fmac_f32_e32 v2, v34, v17
	v_rcp_f32_e32 v34, v3
	v_fma_f32 v3, -v36, v36, 1.0
	v_sqrt_f32_e32 v37, v3
	v_mul_f32_e32 v0, v0, v33
	s_waitcnt lgkmcnt(5)
	v_lshlrev_b32_e32 v19, 16, v38
	v_mul_f32_e32 v3, v0, v19
	v_mul_f32_e32 v33, v1, v18
	v_fmac_f32_e32 v3, v1, v2
	v_mul_f32_e32 v0, v34, v37
	s_waitcnt lgkmcnt(4)
	v_lshlrev_b32_e32 v1, 16, v39
	v_mul_f32_e32 v19, v0, v1
	v_fmamk_f32 v0, v20, 0xbfb8aa3b, v111
	v_exp_f32_e32 v0, v0
	v_fmamk_f32 v1, v4, 0xbfb8aa3b, v113
	v_exp_f32_e32 v1, v1
	v_fmamk_f32 v4, v21, 0xbfb8aa3b, v111
	v_fma_f32 v0, v0, v117, v117
	v_rcp_f32_e32 v0, v0
	v_exp_f32_e32 v20, v4
	v_add_f32_e32 v1, 1.0, v1
	v_fmamk_f32 v5, v5, 0xbfb8aa3b, v113
	v_exp_f32_e32 v4, v0
	v_rcp_f32_e32 v0, v1
	v_fma_f32 v1, v20, v117, v117
	v_rcp_f32_e32 v1, v1
	v_fma_f32 v20, -v4, v4, 1.0
	v_exp_f32_e32 v5, v5
	v_sqrt_f32_e32 v20, v20
	v_exp_f32_e32 v1, v1
	v_add_f32_e32 v5, 1.0, v5
	v_rcp_f32_e32 v21, v5
	v_mul_f32_e32 v0, v0, v20
	v_fma_f32 v5, -v1, v1, 1.0
	v_fmamk_f32 v20, v22, 0xbfb8aa3b, v111
	v_mul_f32_e32 v34, v36, v33
	v_fmac_f32_e32 v19, v36, v3
	v_sqrt_f32_e32 v36, v5
	v_exp_f32_e32 v20, v20
	v_fmamk_f32 v6, v6, 0xbfb8aa3b, v113
	v_exp_f32_e32 v22, v6
	s_waitcnt lgkmcnt(3)
	v_lshlrev_b32_e32 v5, 16, v40
	v_mul_f32_e32 v5, v0, v5
	v_mul_f32_e32 v0, v21, v36
	s_waitcnt lgkmcnt(2)
	v_lshlrev_b32_e32 v21, 16, v41
	v_fma_f32 v6, v20, v117, v117
	v_rcp_f32_e32 v36, v6
	v_mul_f32_e32 v6, v0, v21
	v_add_f32_e32 v0, 1.0, v22
	v_fmamk_f32 v22, v23, 0xbfb8aa3b, v111
	v_exp_f32_e32 v22, v22
	v_mul_f32_e32 v20, v1, v4
	v_mov_b32_e32 v21, v36
	v_fmac_f32_e32 v6, v1, v5
	v_fma_f32 v1, v22, v117, v117
	v_exp_f32_e32 v21, v21
	v_rcp_f32_e32 v1, v1
	v_fmamk_f32 v7, v7, 0xbfb8aa3b, v113
	v_exp_f32_e32 v7, v7
	v_fma_f32 v23, -v21, v21, 1.0
	v_rcp_f32_e32 v0, v0
	v_sqrt_f32_e32 v23, v23
	v_exp_f32_e32 v1, v1
	v_add_f32_e32 v7, 1.0, v7
	s_waitcnt lgkmcnt(1)
	v_lshlrev_b32_e32 v22, 16, v42
	v_mul_f32_e32 v0, v0, v23
	v_rcp_f32_e32 v23, v7
	v_fma_f32 v7, -v1, v1, 1.0
	v_sqrt_f32_e32 v36, v7
	v_mul_f32_e32 v7, v0, v22
	v_mul_f32_e32 v22, v21, v20
	v_fmac_f32_e32 v7, v21, v6
	v_mul_f32_e32 v0, v23, v36
	s_waitcnt lgkmcnt(0)
	v_lshlrev_b32_e32 v21, 16, v43
	v_mul_f32_e32 v21, v0, v21
	v_fmamk_f32 v0, v24, 0xbfb8aa3b, v111
	v_exp_f32_e32 v0, v0
	v_fmamk_f32 v8, v8, 0xbfb8aa3b, v113
	v_exp_f32_e32 v8, v8
	v_mul_f32_e32 v23, v1, v22
	v_fma_f32 v0, v0, v117, v117
	v_fmac_f32_e32 v21, v1, v7
	v_rcp_f32_e32 v0, v0
	v_add_f32_e32 v1, 1.0, v8
	v_fmamk_f32 v8, v25, 0xbfb8aa3b, v111
	v_exp_f32_e32 v24, v8
	v_exp_f32_e32 v8, v0
	v_rcp_f32_e32 v0, v1
	v_fma_f32 v1, v24, v117, v117
	v_rcp_f32_e32 v1, v1
	v_fmamk_f32 v9, v9, 0xbfb8aa3b, v113
	v_fma_f32 v24, -v8, v8, 1.0
	v_exp_f32_e32 v9, v9
	v_exp_f32_e32 v1, v1
	v_sqrt_f32_e32 v24, v24
	v_add_f32_e32 v9, 1.0, v9
	v_rcp_f32_e32 v25, v9
	v_fma_f32 v9, -v1, v1, 1.0
	v_mul_f32_e32 v0, v0, v24
	v_fmamk_f32 v24, v26, 0xbfb8aa3b, v111
	v_sqrt_f32_e32 v36, v9
	v_exp_f32_e32 v24, v24
	v_fmamk_f32 v10, v10, 0xbfb8aa3b, v113
	v_exp_f32_e32 v26, v10
	ds_read_u16 v9, v35 offset:20736
	ds_read_u16 v37, v35 offset:20880
	ds_read_u16 v38, v35 offset:21024
	ds_read_u16 v39, v35 offset:21168
	ds_read_u16 v40, v35 offset:21888
	ds_read_u16 v41, v35 offset:22032
	ds_read_u16 v42, v35 offset:22176
	ds_read_u16 v35, v35 offset:22320
	s_waitcnt lgkmcnt(7)
	v_lshlrev_b32_e32 v9, 16, v9
	v_mul_f32_e32 v9, v0, v9
	v_mul_f32_e32 v0, v25, v36
	s_waitcnt lgkmcnt(6)
	v_lshlrev_b32_e32 v25, 16, v37
	v_fma_f32 v10, v24, v117, v117
	v_rcp_f32_e32 v36, v10
	v_mul_f32_e32 v10, v0, v25
	v_add_f32_e32 v0, 1.0, v26
	v_fmamk_f32 v26, v27, 0xbfb8aa3b, v111
	v_exp_f32_e32 v26, v26
	v_mul_f32_e32 v24, v1, v8
	v_mov_b32_e32 v25, v36
	v_fmac_f32_e32 v10, v1, v9
	v_fma_f32 v1, v26, v117, v117
	v_exp_f32_e32 v25, v25
	v_rcp_f32_e32 v1, v1
	v_fmamk_f32 v11, v11, 0xbfb8aa3b, v113
	v_exp_f32_e32 v11, v11
	v_fma_f32 v27, -v25, v25, 1.0
	v_rcp_f32_e32 v0, v0
	v_sqrt_f32_e32 v27, v27
	v_exp_f32_e32 v1, v1
	v_add_f32_e32 v11, 1.0, v11
	s_waitcnt lgkmcnt(5)
	v_lshlrev_b32_e32 v26, 16, v38
	v_mul_f32_e32 v0, v0, v27
	v_rcp_f32_e32 v27, v11
	v_fma_f32 v11, -v1, v1, 1.0
	v_sqrt_f32_e32 v36, v11
	v_mul_f32_e32 v11, v0, v26
	v_mul_f32_e32 v26, v25, v24
	v_fmac_f32_e32 v11, v25, v10
	v_mul_f32_e32 v0, v27, v36
	s_waitcnt lgkmcnt(4)
	v_lshlrev_b32_e32 v25, 16, v39
	v_mul_f32_e32 v25, v0, v25
	v_fmamk_f32 v0, v28, 0xbfb8aa3b, v111
	v_exp_f32_e32 v0, v0
	v_fmamk_f32 v12, v12, 0xbfb8aa3b, v113
	v_exp_f32_e32 v12, v12
	v_mul_f32_e32 v27, v1, v26
	v_fma_f32 v0, v0, v117, v117
	v_fmac_f32_e32 v25, v1, v11
	v_rcp_f32_e32 v0, v0
	v_add_f32_e32 v1, 1.0, v12
	v_fmamk_f32 v12, v29, 0xbfb8aa3b, v111
	v_exp_f32_e32 v28, v12
	v_exp_f32_e32 v12, v0
	v_rcp_f32_e32 v0, v1
	v_fma_f32 v1, v28, v117, v117
	v_rcp_f32_e32 v1, v1
	v_fmamk_f32 v13, v13, 0xbfb8aa3b, v113
	v_fma_f32 v28, -v12, v12, 1.0
	v_exp_f32_e32 v13, v13
	v_exp_f32_e32 v1, v1
	v_sqrt_f32_e32 v28, v28
	v_add_f32_e32 v13, 1.0, v13
	v_rcp_f32_e32 v29, v13
	v_fma_f32 v13, -v1, v1, 1.0
	v_mul_f32_e32 v0, v0, v28
	v_fmamk_f32 v28, v30, 0xbfb8aa3b, v111
	v_sqrt_f32_e32 v36, v13
	v_exp_f32_e32 v28, v28
	v_fmamk_f32 v14, v14, 0xbfb8aa3b, v113
	v_exp_f32_e32 v30, v14
	s_waitcnt lgkmcnt(3)
	v_lshlrev_b32_e32 v13, 16, v40
	v_mul_f32_e32 v13, v0, v13
	v_mul_f32_e32 v0, v29, v36
	s_waitcnt lgkmcnt(2)
	v_lshlrev_b32_e32 v29, 16, v41
	v_fma_f32 v14, v28, v117, v117
	v_fmac_f32_e32 v111, 0xbfb8aa3b, v31
	v_rcp_f32_e32 v36, v14
	v_mul_f32_e32 v14, v0, v29
	v_add_f32_e32 v0, 1.0, v30
	v_exp_f32_e32 v30, v111
	v_mul_f32_e32 v28, v1, v12
	v_mov_b32_e32 v29, v36
	v_fmac_f32_e32 v14, v1, v13
	v_fma_f32 v1, v30, v117, v117
	v_exp_f32_e32 v29, v29
	v_rcp_f32_e32 v1, v1
	v_fmac_f32_e32 v113, 0xbfb8aa3b, v15
	v_exp_f32_e32 v15, v113
	v_fma_f32 v31, -v29, v29, 1.0
	v_rcp_f32_e32 v0, v0
	v_sqrt_f32_e32 v31, v31
	v_exp_f32_e32 v1, v1
	v_add_f32_e32 v15, 1.0, v15
	s_waitcnt lgkmcnt(1)
	v_lshlrev_b32_e32 v30, 16, v42
	v_mul_f32_e32 v0, v0, v31
	v_rcp_f32_e32 v31, v15
	v_fma_f32 v15, -v1, v1, 1.0
	v_sqrt_f32_e32 v36, v15
	v_mul_f32_e32 v15, v0, v30
	v_mul_f32_e32 v30, v29, v28
	v_fmac_f32_e32 v15, v29, v14
	v_mul_f32_e32 v0, v31, v36
	s_waitcnt lgkmcnt(0)
	v_lshlrev_b32_e32 v29, 16, v35
	v_mul_f32_e32 v29, v0, v29
	ds_bpermute_b32 v35, v115, v34
	ds_bpermute_b32 v0, v115, v19
	ds_bpermute_b32 v41, v115, v23
	ds_bpermute_b32 v42, v115, v21
	ds_bpermute_b32 v45, v115, v27
	ds_bpermute_b32 v46, v115, v25
	v_mul_f32_e32 v31, v1, v30
	v_fmac_f32_e32 v29, v1, v15
	s_waitcnt lgkmcnt(5)
	v_cndmask_b32_e64 v39, v35, v34, s[4:5]
	s_waitcnt lgkmcnt(4)
	v_cndmask_b32_e64 v36, v0, v19, s[4:5]
	ds_bpermute_b32 v38, v115, v31
	ds_bpermute_b32 v1, v115, v29
	v_cndmask_b32_e64 v40, v34, v35, s[4:5]
	v_cndmask_b32_e64 v37, v19, v0, s[4:5]
	v_fmac_f32_e32 v36, 0, v39
	v_fmac_f32_e32 v37, v40, v36
	v_mul_f32_e32 v39, v34, v35
	s_waitcnt lgkmcnt(5)
	v_cndmask_b32_e64 v0, v41, v23, s[4:5]
	s_waitcnt lgkmcnt(4)
	v_cndmask_b32_e64 v40, v42, v21, s[4:5]
	v_cndmask_b32_e64 v43, v23, v41, s[4:5]
	v_cndmask_b32_e64 v41, v21, v42, s[4:5]
	v_fmac_f32_e32 v40, v0, v37
	v_mul_f32_e32 v42, v39, v0
	v_fmac_f32_e32 v41, v43, v40
	v_mul_f32_e32 v43, v43, v42
	s_waitcnt lgkmcnt(3)
	v_cndmask_b32_e64 v0, v45, v27, s[4:5]
	s_waitcnt lgkmcnt(2)
	v_cndmask_b32_e64 v44, v46, v25, s[4:5]
	v_cndmask_b32_e64 v47, v27, v45, s[4:5]
	v_cndmask_b32_e64 v45, v25, v46, s[4:5]
	v_fmac_f32_e32 v44, v0, v41
	v_mul_f32_e32 v46, v43, v0
	v_fmac_f32_e32 v45, v47, v44
	v_mul_f32_e32 v47, v47, v46
	s_waitcnt lgkmcnt(1)
	v_cndmask_b32_e64 v0, v38, v31, s[4:5]
	s_waitcnt lgkmcnt(0)
	v_cndmask_b32_e64 v48, v1, v29, s[4:5]
	v_fmac_f32_e32 v48, v0, v45
	v_mul_f32_e32 v49, v47, v0
	s_and_saveexec_b64 s[46:47], s[4:5]
	s_cbranch_execz .LBB0_305
	v_mul_f32_e32 v0, v49, v38
	v_fmac_f32_e32 v1, v38, v48
	ds_write_b64 v119, v[0:1] offset:38912
	s_branch .LBB0_305

.LBB0_690:
	v_fmamk_f32 v144, v166, 0x3a800000, v151
	v_mov_b32_e32 v200, v144
	v_rsq_f32_e32 v145, v144
	v_pk_mul_f32 v[120:121], v[124:125], v[120:121]
	v_pk_mul_f32 v[122:123], v[126:127], v[122:123]
	v_pk_mul_f32 v[112:113], v[116:117], v[112:113]
	v_mul_f32_e32 v166, 0xbfb8aa3b, v145
	v_pk_mul_f32 v[168:169], v[166:167], v[124:125] op_sel_hi:[0,1]
	v_exp_f32_e32 v168, v168
	v_exp_f32_e32 v169, v169
	v_pk_mul_f32 v[124:125], v[166:167], v[126:127] op_sel_hi:[0,1]
	v_exp_f32_e32 v124, v124
	v_exp_f32_e32 v125, v125
	v_pk_fma_f32 v[168:169], v[168:169], v[200:201], v[200:201] op_sel_hi:[1,0,0]
	v_rcp_f32_e32 v168, v168
	v_rcp_f32_e32 v169, v169
	v_pk_fma_f32 v[124:125], v[124:125], v[200:201], v[200:201] op_sel_hi:[1,0,0]
	v_pk_mul_f32 v[114:115], v[118:119], v[114:115]
	v_rcp_f32_e32 v124, v124
	v_rcp_f32_e32 v125, v125
	v_pk_mul_f32 v[120:121], v[168:169], v[120:121]
	v_pk_mul_f32 v[126:127], v[166:167], v[116:117] op_sel_hi:[0,1]
	v_exp_f32_e32 v126, v126
	v_exp_f32_e32 v127, v127
	v_pk_mul_f32 v[122:123], v[124:125], v[122:123]
	v_pk_mul_f32 v[124:125], v[166:167], v[118:119] op_sel_hi:[0,1]
	v_exp_f32_e32 v124, v124
	v_exp_f32_e32 v125, v125
	v_cvt_pk_bf16_f32 v120, v120, v121
	v_cvt_pk_bf16_f32 v121, v122, v123
	v_pk_fma_f32 v[122:123], v[126:127], v[200:201], v[200:201] op_sel_hi:[1,0,0]
	v_pk_fma_f32 v[116:117], v[124:125], v[200:201], v[200:201] op_sel_hi:[1,0,0]
	v_rcp_f32_e32 v122, v122
	v_rcp_f32_e32 v123, v123
	v_rcp_f32_e32 v116, v116
	v_rcp_f32_e32 v117, v117
	v_lshl_or_b32 v170, s18, 7, v148
	v_pk_mul_f32 v[112:113], v[122:123], v[112:113]
	v_lshl_add_u32 v144, s36, 8, v146
	v_cvt_pk_bf16_f32 v122, v112, v113
	v_pk_mul_f32 v[112:113], v[116:117], v[114:115]
	v_fmamk_f32 v114, v165, 0x3a800000, v151
	v_mov_b32_e32 v202, v114
	v_rsq_f32_e32 v119, v114
	v_ashrrev_i32_e32 v171, 31, v170
	v_cvt_pk_bf16_f32 v123, v112, v113
	v_mov_b64_e32 v[112:113], s[34:35]
	v_mul_f32_e32 v118, 0xbfb8aa3b, v119
	v_pk_mul_f32 v[124:125], v[118:119], v[108:109] op_sel_hi:[0,1]
	v_exp_f32_e32 v124, v124
	v_exp_f32_e32 v125, v125
	v_pk_mul_f32 v[104:105], v[108:109], v[104:105]
	v_pk_mul_f32 v[108:109], v[118:119], v[110:111] op_sel_hi:[0,1]
	v_mad_i64_i32 v[116:117], s[18:19], v144, s56, v[112:113]
	v_lshlrev_b64 v[114:115], 1, v[170:171]
	v_exp_f32_e32 v108, v108
	v_exp_f32_e32 v109, v109
	v_lshl_add_u64 v[216:217], v[116:117], 0, v[114:115]
	global_store_dwordx4 v[216:217], v[120:123], off
	s_mov_b32 s99, 0
	s_nop 0
	v_pk_fma_f32 v[108:109], v[108:109], v[202:203], v[202:203] op_sel_hi:[1,0,0]
	v_pk_fma_f32 v[120:121], v[124:125], v[202:203], v[202:203] op_sel_hi:[1,0,0]
	v_rcp_f32_e32 v108, v108
	v_rcp_f32_e32 v120, v120
	v_rcp_f32_e32 v121, v121
	v_rcp_f32_e32 v109, v109
	v_pk_mul_f32 v[106:107], v[110:111], v[106:107]
	v_pk_mul_f32 v[96:97], v[100:101], v[96:97]
	v_pk_mul_f32 v[104:105], v[120:121], v[104:105]
	v_pk_mul_f32 v[110:111], v[118:119], v[100:101] op_sel_hi:[0,1]
	v_exp_f32_e32 v110, v110
	v_exp_f32_e32 v111, v111
	v_pk_mul_f32 v[106:107], v[108:109], v[106:107]
	v_pk_mul_f32 v[108:109], v[118:119], v[102:103] op_sel_hi:[0,1]
	v_exp_f32_e32 v108, v108
	v_exp_f32_e32 v109, v109
	v_cvt_pk_bf16_f32 v104, v104, v105
	v_cvt_pk_bf16_f32 v105, v106, v107
	v_pk_fma_f32 v[106:107], v[110:111], v[202:203], v[202:203] op_sel_hi:[1,0,0]
	v_pk_fma_f32 v[100:101], v[108:109], v[202:203], v[202:203] op_sel_hi:[1,0,0]
	v_rcp_f32_e32 v106, v106
	v_rcp_f32_e32 v107, v107
	v_rcp_f32_e32 v100, v100
	v_rcp_f32_e32 v101, v101
	v_pk_mul_f32 v[98:99], v[102:103], v[98:99]
	v_pk_mul_f32 v[96:97], v[106:107], v[96:97]
	v_pk_mul_f32 v[88:89], v[92:93], v[88:89]
	v_cvt_pk_bf16_f32 v106, v96, v97
	v_pk_mul_f32 v[96:97], v[100:101], v[98:99]
	v_pk_mul_f32 v[90:91], v[94:95], v[90:91]
	v_cvt_pk_bf16_f32 v107, v96, v97
	v_fmamk_f32 v96, v164, 0x3a800000, v151
	v_mov_b32_e32 v204, v96
	v_rsq_f32_e32 v99, v96
	s_nop 0
	v_mul_f32_e32 v98, 0xbfb8aa3b, v99
	v_pk_mul_f32 v[100:101], v[98:99], v[92:93] op_sel_hi:[0,1]
	v_exp_f32_e32 v100, v100
	v_exp_f32_e32 v101, v101
	v_pk_mul_f32 v[92:93], v[98:99], v[94:95] op_sel_hi:[0,1]
	v_exp_f32_e32 v92, v92
	v_exp_f32_e32 v93, v93
	v_pk_fma_f32 v[100:101], v[100:101], v[204:205], v[204:205] op_sel_hi:[1,0,0]
	s_mov_b32 s98, 0x16000
	v_lshl_add_u64 v[96:97], v[216:217], 0, s[98:99]
	v_rcp_f32_e32 v100, v100
	v_rcp_f32_e32 v101, v101
	v_pk_fma_f32 v[92:93], v[92:93], v[204:205], v[204:205] op_sel_hi:[1,0,0]
	global_store_dwordx4 v[96:97], v[104:107], off
	v_rcp_f32_e32 v92, v92
	v_rcp_f32_e32 v93, v93
	v_pk_mul_f32 v[88:89], v[100:101], v[88:89]
	v_pk_mul_f32 v[94:95], v[98:99], v[84:85] op_sel_hi:[0,1]
	v_exp_f32_e32 v94, v94
	v_exp_f32_e32 v95, v95
	v_pk_mul_f32 v[90:91], v[92:93], v[90:91]
	v_pk_mul_f32 v[92:93], v[98:99], v[86:87] op_sel_hi:[0,1]
	v_exp_f32_e32 v92, v92
	v_exp_f32_e32 v93, v93
	v_cvt_pk_bf16_f32 v88, v88, v89
	v_cvt_pk_bf16_f32 v89, v90, v91
	v_pk_fma_f32 v[90:91], v[94:95], v[204:205], v[204:205] op_sel_hi:[1,0,0]
	v_pk_mul_f32 v[80:81], v[84:85], v[80:81]
	v_rcp_f32_e32 v90, v90
	v_rcp_f32_e32 v91, v91
	v_pk_fma_f32 v[84:85], v[92:93], v[204:205], v[204:205] op_sel_hi:[1,0,0]
	v_pk_mul_f32 v[82:83], v[86:87], v[82:83]
	v_rcp_f32_e32 v84, v84
	v_rcp_f32_e32 v85, v85
	v_pk_mul_f32 v[80:81], v[90:91], v[80:81]
	v_pk_mul_f32 v[72:73], v[76:77], v[72:73]
	v_cvt_pk_bf16_f32 v90, v80, v81
	v_pk_mul_f32 v[80:81], v[84:85], v[82:83]
	v_pk_mul_f32 v[74:75], v[78:79], v[74:75]
	v_cvt_pk_bf16_f32 v91, v80, v81
	v_fmamk_f32 v80, v163, 0x3a800000, v151
	v_mov_b32_e32 v206, v80
	v_rsq_f32_e32 v83, v80
	s_nop 0
	v_mul_f32_e32 v82, 0xbfb8aa3b, v83
	v_pk_mul_f32 v[84:85], v[82:83], v[76:77] op_sel_hi:[0,1]
	v_exp_f32_e32 v84, v84
	v_exp_f32_e32 v85, v85
	v_pk_mul_f32 v[76:77], v[82:83], v[78:79] op_sel_hi:[0,1]
	v_exp_f32_e32 v76, v76
	v_exp_f32_e32 v77, v77
	v_pk_fma_f32 v[84:85], v[84:85], v[206:207], v[206:207] op_sel_hi:[1,0,0]
	s_mov_b32 s98, 0x2c000
	v_lshl_add_u64 v[80:81], v[216:217], 0, s[98:99]
	v_rcp_f32_e32 v84, v84
	v_rcp_f32_e32 v85, v85
	v_pk_fma_f32 v[76:77], v[76:77], v[206:207], v[206:207] op_sel_hi:[1,0,0]
	global_store_dwordx4 v[80:81], v[88:91], off
	v_rcp_f32_e32 v76, v76
	v_rcp_f32_e32 v77, v77
	v_pk_mul_f32 v[72:73], v[84:85], v[72:73]
	v_pk_mul_f32 v[78:79], v[82:83], v[68:69] op_sel_hi:[0,1]
	v_exp_f32_e32 v78, v78
	v_exp_f32_e32 v79, v79
	v_pk_mul_f32 v[74:75], v[76:77], v[74:75]
	v_pk_mul_f32 v[76:77], v[82:83], v[70:71] op_sel_hi:[0,1]
	v_exp_f32_e32 v76, v76
	v_exp_f32_e32 v77, v77
	v_cvt_pk_bf16_f32 v72, v72, v73
	v_cvt_pk_bf16_f32 v73, v74, v75
	v_pk_fma_f32 v[74:75], v[78:79], v[206:207], v[206:207] op_sel_hi:[1,0,0]
	v_pk_mul_f32 v[64:65], v[68:69], v[64:65]
	v_rcp_f32_e32 v74, v74
	v_rcp_f32_e32 v75, v75
	v_pk_fma_f32 v[68:69], v[76:77], v[206:207], v[206:207] op_sel_hi:[1,0,0]
	v_pk_mul_f32 v[66:67], v[70:71], v[66:67]
	v_rcp_f32_e32 v68, v68
	v_rcp_f32_e32 v69, v69
	v_pk_mul_f32 v[64:65], v[74:75], v[64:65]
	v_pk_mul_f32 v[56:57], v[60:61], v[56:57]
	v_cvt_pk_bf16_f32 v74, v64, v65
	v_pk_mul_f32 v[64:65], v[68:69], v[66:67]
	v_pk_mul_f32 v[58:59], v[62:63], v[58:59]
	v_cvt_pk_bf16_f32 v75, v64, v65
	v_fmamk_f32 v65, v162, 0x3a800000, v151
	v_mov_b32_e32 v208, v65
	v_rsq_f32_e32 v67, v65
	s_nop 0
	v_mul_f32_e32 v66, 0xbfb8aa3b, v67
	v_pk_mul_f32 v[68:69], v[66:67], v[60:61] op_sel_hi:[0,1]
	v_exp_f32_e32 v68, v68
	v_exp_f32_e32 v69, v69
	v_pk_mul_f32 v[60:61], v[66:67], v[62:63] op_sel_hi:[0,1]
	v_exp_f32_e32 v60, v60
	v_exp_f32_e32 v61, v61
	v_pk_fma_f32 v[68:69], v[68:69], v[208:209], v[208:209] op_sel_hi:[1,0,0]
	s_mov_b32 s98, 0x42000
	v_lshl_add_u64 v[64:65], v[216:217], 0, s[98:99]
	v_rcp_f32_e32 v68, v68
	v_rcp_f32_e32 v69, v69
	v_pk_fma_f32 v[60:61], v[60:61], v[208:209], v[208:209] op_sel_hi:[1,0,0]
	global_store_dwordx4 v[64:65], v[72:75], off
	v_rcp_f32_e32 v60, v60
	v_rcp_f32_e32 v61, v61
	v_pk_mul_f32 v[56:57], v[68:69], v[56:57]
	v_pk_mul_f32 v[62:63], v[66:67], v[52:53] op_sel_hi:[0,1]
	v_exp_f32_e32 v62, v62
	v_exp_f32_e32 v63, v63
	v_pk_mul_f32 v[58:59], v[60:61], v[58:59]
	v_pk_mul_f32 v[60:61], v[66:67], v[54:55] op_sel_hi:[0,1]
	v_exp_f32_e32 v60, v60
	v_exp_f32_e32 v61, v61
	v_cvt_pk_bf16_f32 v56, v56, v57
	v_cvt_pk_bf16_f32 v57, v58, v59
	v_pk_fma_f32 v[58:59], v[62:63], v[208:209], v[208:209] op_sel_hi:[1,0,0]
	v_pk_mul_f32 v[48:49], v[52:53], v[48:49]
	v_rcp_f32_e32 v58, v58
	v_rcp_f32_e32 v59, v59
	v_pk_fma_f32 v[52:53], v[60:61], v[208:209], v[208:209] op_sel_hi:[1,0,0]
	v_pk_mul_f32 v[50:51], v[54:55], v[50:51]
	v_rcp_f32_e32 v52, v52
	v_rcp_f32_e32 v53, v53
	v_pk_mul_f32 v[48:49], v[58:59], v[48:49]
	v_pk_mul_f32 v[40:41], v[44:45], v[40:41]
	v_cvt_pk_bf16_f32 v58, v48, v49
	v_pk_mul_f32 v[48:49], v[52:53], v[50:51]
	v_fmamk_f32 v50, v161, 0x3a800000, v151
	v_mov_b32_e32 v210, v50
	v_rsq_f32_e32 v51, v50
	v_cvt_pk_bf16_f32 v59, v48, v49
	v_mul_f32_e32 v50, 0xbfb8aa3b, v51
	v_pk_mul_f32 v[52:53], v[50:51], v[44:45] op_sel_hi:[0,1]
	v_exp_f32_e32 v52, v52
	v_exp_f32_e32 v53, v53
	v_pk_mul_f32 v[44:45], v[50:51], v[46:47] op_sel_hi:[0,1]
	v_exp_f32_e32 v44, v44
	v_exp_f32_e32 v45, v45
	v_pk_fma_f32 v[52:53], v[52:53], v[210:211], v[210:211] op_sel_hi:[1,0,0]
	s_mov_b32 s98, 0xb0000
	v_lshl_add_u64 v[48:49], v[216:217], 0, s[98:99]
	v_rcp_f32_e32 v52, v52
	v_rcp_f32_e32 v53, v53
	v_pk_fma_f32 v[44:45], v[44:45], v[210:211], v[210:211] op_sel_hi:[1,0,0]
	global_store_dwordx4 v[48:49], v[56:59], off
	v_rcp_f32_e32 v44, v44
	v_rcp_f32_e32 v45, v45
	v_pk_mul_f32 v[42:43], v[46:47], v[42:43]
	v_pk_mul_f32 v[40:41], v[52:53], v[40:41]
	v_pk_mul_f32 v[46:47], v[50:51], v[36:37] op_sel_hi:[0,1]
	v_exp_f32_e32 v46, v46
	v_exp_f32_e32 v47, v47
	v_pk_mul_f32 v[42:43], v[44:45], v[42:43]
	v_pk_mul_f32 v[44:45], v[50:51], v[38:39] op_sel_hi:[0,1]
	v_exp_f32_e32 v44, v44
	v_exp_f32_e32 v45, v45
	v_cvt_pk_bf16_f32 v40, v40, v41
	v_cvt_pk_bf16_f32 v41, v42, v43
	v_pk_fma_f32 v[42:43], v[46:47], v[210:211], v[210:211] op_sel_hi:[1,0,0]
	v_pk_mul_f32 v[32:33], v[36:37], v[32:33]
	v_rcp_f32_e32 v42, v42
	v_rcp_f32_e32 v43, v43
	v_pk_fma_f32 v[36:37], v[44:45], v[210:211], v[210:211] op_sel_hi:[1,0,0]
	v_pk_mul_f32 v[34:35], v[38:39], v[34:35]
	v_rcp_f32_e32 v36, v36
	v_rcp_f32_e32 v37, v37
	v_pk_mul_f32 v[32:33], v[42:43], v[32:33]
	v_pk_mul_f32 v[24:25], v[28:29], v[24:25]
	v_cvt_pk_bf16_f32 v42, v32, v33
	v_pk_mul_f32 v[32:33], v[36:37], v[34:35]
	v_pk_mul_f32 v[26:27], v[30:31], v[26:27]
	v_cvt_pk_bf16_f32 v43, v32, v33
	v_fmamk_f32 v32, v152, 0x3a800000, v151
	v_mov_b32_e32 v212, v32
	v_rsq_f32_e32 v35, v32
	s_nop 0
	v_mul_f32_e32 v34, 0xbfb8aa3b, v35
	v_pk_mul_f32 v[36:37], v[34:35], v[28:29] op_sel_hi:[0,1]
	v_exp_f32_e32 v36, v36
	v_exp_f32_e32 v37, v37
	v_pk_mul_f32 v[28:29], v[34:35], v[30:31] op_sel_hi:[0,1]
	v_exp_f32_e32 v28, v28
	v_exp_f32_e32 v29, v29
	v_pk_fma_f32 v[36:37], v[36:37], v[212:213], v[212:213] op_sel_hi:[1,0,0]
	s_mov_b32 s98, 0xc6000
	v_lshl_add_u64 v[32:33], v[216:217], 0, s[98:99]
	v_rcp_f32_e32 v36, v36
	v_rcp_f32_e32 v37, v37
	v_pk_fma_f32 v[28:29], v[28:29], v[212:213], v[212:213] op_sel_hi:[1,0,0]
	global_store_dwordx4 v[32:33], v[40:43], off
	v_rcp_f32_e32 v28, v28
	v_rcp_f32_e32 v29, v29
	v_pk_mul_f32 v[24:25], v[36:37], v[24:25]
	v_pk_mul_f32 v[30:31], v[34:35], v[20:21] op_sel_hi:[0,1]
	v_exp_f32_e32 v30, v30
	v_exp_f32_e32 v31, v31
	v_pk_mul_f32 v[26:27], v[28:29], v[26:27]
	v_pk_mul_f32 v[28:29], v[34:35], v[22:23] op_sel_hi:[0,1]
	v_exp_f32_e32 v28, v28
	v_exp_f32_e32 v29, v29
	v_cvt_pk_bf16_f32 v24, v24, v25
	v_cvt_pk_bf16_f32 v25, v26, v27
	v_pk_fma_f32 v[26:27], v[30:31], v[212:213], v[212:213] op_sel_hi:[1,0,0]
	v_pk_mul_f32 v[16:17], v[20:21], v[16:17]
	v_rcp_f32_e32 v26, v26
	v_rcp_f32_e32 v27, v27
	v_pk_fma_f32 v[20:21], v[28:29], v[212:213], v[212:213] op_sel_hi:[1,0,0]
	v_pk_mul_f32 v[18:19], v[22:23], v[18:19]
	v_rcp_f32_e32 v20, v20
	v_rcp_f32_e32 v21, v21
	v_pk_mul_f32 v[16:17], v[26:27], v[16:17]
	v_pk_mul_f32 v[8:9], v[12:13], v[8:9]
	v_cvt_pk_bf16_f32 v26, v16, v17
	v_pk_mul_f32 v[16:17], v[20:21], v[18:19]
	v_pk_mul_f32 v[10:11], v[14:15], v[10:11]
	v_cvt_pk_bf16_f32 v27, v16, v17
	v_fmamk_f32 v16, v149, 0x3a800000, v151
	v_mov_b32_e32 v214, v16
	v_rsq_f32_e32 v19, v16
	s_nop 0
	v_mul_f32_e32 v18, 0xbfb8aa3b, v19
	v_pk_mul_f32 v[20:21], v[18:19], v[12:13] op_sel_hi:[0,1]
	v_exp_f32_e32 v20, v20
	v_exp_f32_e32 v21, v21
	v_pk_mul_f32 v[12:13], v[18:19], v[14:15] op_sel_hi:[0,1]
	v_exp_f32_e32 v12, v12
	v_exp_f32_e32 v13, v13
	v_pk_fma_f32 v[20:21], v[20:21], v[214:215], v[214:215] op_sel_hi:[1,0,0]
	s_mov_b32 s98, 0xdc000
	v_lshl_add_u64 v[16:17], v[216:217], 0, s[98:99]
	v_rcp_f32_e32 v20, v20
	v_rcp_f32_e32 v21, v21
	v_pk_fma_f32 v[12:13], v[12:13], v[214:215], v[214:215] op_sel_hi:[1,0,0]
	global_store_dwordx4 v[16:17], v[24:27], off
	v_rcp_f32_e32 v12, v12
	v_rcp_f32_e32 v13, v13
	v_pk_mul_f32 v[8:9], v[20:21], v[8:9]
	v_pk_mul_f32 v[14:15], v[18:19], v[4:5] op_sel_hi:[0,1]
	v_exp_f32_e32 v14, v14
	v_exp_f32_e32 v15, v15
	v_pk_mul_f32 v[10:11], v[12:13], v[10:11]
	v_pk_mul_f32 v[12:13], v[18:19], v[6:7] op_sel_hi:[0,1]
	v_exp_f32_e32 v12, v12
	v_exp_f32_e32 v13, v13
	v_cvt_pk_bf16_f32 v8, v8, v9
	v_cvt_pk_bf16_f32 v9, v10, v11
	v_pk_fma_f32 v[10:11], v[14:15], v[214:215], v[214:215] op_sel_hi:[1,0,0]
	v_pk_mul_f32 v[0:1], v[4:5], v[0:1]
	v_rcp_f32_e32 v10, v10
	v_rcp_f32_e32 v11, v11
	v_pk_fma_f32 v[4:5], v[12:13], v[214:215], v[214:215] op_sel_hi:[1,0,0]
	v_pk_mul_f32 v[2:3], v[6:7], v[2:3]
	v_rcp_f32_e32 v4, v4
	v_rcp_f32_e32 v5, v5
	v_pk_mul_f32 v[0:1], v[10:11], v[0:1]
	s_andn2_b64 vcc, exec, s[0:1]
	v_cvt_pk_bf16_f32 v10, v0, v1
	v_pk_mul_f32 v[0:1], v[4:5], v[2:3]
	s_mov_b64 s[0:1], -1
	v_cvt_pk_bf16_f32 v11, v0, v1
	s_mov_b32 s98, 0xf2000
	v_lshl_add_u64 v[0:1], v[216:217], 0, s[98:99]
	global_store_dwordx4 v[0:1], v[8:11], off
	s_cbranch_vccnz .LBB0_681
	s_andn2_b64 vcc, exec, s[6:7]
	s_cbranch_vccnz .LBB0_680
	s_barrier
	s_branch .LBB0_680
